# K-loops: s_setprio 1 moved before the phase barrier, redundant lgkmcnt(0) behind it dropped, closing barrier signalled before s_setprio 0; on top of the write-through version
# speedup vs baseline: 1.0178x; 1.0178x over previous
; #define PG8_STAGE(bufoff, gbase, voff) do { _Pragma("unroll") for (int _i = 0; _i < 2; ++_i) \
;         __builtin_amdgcn_global_load_lds((const unsigned*)((const char*)(gbase) + (voff)[_i]), (LAS unsigned*)(lds + (bufoff) + ldsw + _i * 8192), 16, 0, 0); } while (0)
; #define PG8_LDA(dst, b, h) do { _Pragma("unroll") for (int m = 0; m < 4; ++m) _Pragma("unroll") for (int k = 0; k < 2; ++k) dst[m][k] = *(const LAS bf16x8*)(lds + PG8_SA(b, h) + aoff + m * 2048 + k * 1024); } while (0)
; #define PG8_LDB(dst, b, h) do { _Pragma("unroll") for (int n = 0; n < 2; ++n) _Pragma("unroll") for (int k = 0; k < 2; ++k) dst[n][k] = *(const LAS bf16x8*)(lds + PG8_SB(b, h) + boff + n * 2048 + k * 1024); } while (0)
; #define PG8_MMA(ai, bj, At, Bt) do { __builtin_amdgcn_s_setprio(1); _Pragma("unroll") for (int m = 0; m < 4; ++m) _Pragma("unroll") for (int n = 0; n < 2; ++n) _Pragma("unroll") for (int k = 0; k < 2; ++k) \
;         acc[ai][bj][m][n] = __builtin_amdgcn_mfma_f32_16x16x32_bf16(Bt[n][k], At[m][k], acc[ai][bj][m][n], 0, 0, 0); __builtin_amdgcn_s_setprio(0); } while (0)
; #define PG8_WAIT_V(n) asm volatile("s_waitcnt vmcnt(" #n ")" ::: "memory")
; #define PG8_WAIT_L(n) asm volatile("s_waitcnt lgkmcnt(" #n ")" ::: "memory")
; #define PG8_BAR __builtin_amdgcn_s_barrier()
; #define PG8_SCHED __builtin_amdgcn_sched_barrier(0)
; template <class Epi, class Sched>
; __device__ __forceinline__ void gemm_phase(LAS unsigned char* lds, const int K, const Sched& S, const Epi& E) {
;     ...
;             const bool last = (t == nt - 2);
;             const char* a1 = cA + (size_t)(t + 1) * kstep;
;             const char* a2 = last ? nA : cA + (size_t)(t + 2) * kstep; const char* b2 = last ? nB : cB + (size_t)(t + 2) * kstep;
;             const char* a3 = a2 + kstep; const char* b3 = b2 + kstep;
;             PG8_LDB(B0, 0, 0); PG8_LDB(B1, 0, 1); PG8_SCHED; PG8_LDA(At, 0, 0); PG8_STAGE(PG8_SA(1, 1), a1 + hstep, voffA);
;             PG8_WAIT_V(8); PG8_WAIT_L(0); PG8_BAR; PG8_MMA(0, 0, At, B0); PG8_MMA(0, 1, At, B1); PG8_BAR; PG8_SCHED;
;             PG8_LDA(At, 0, 1); PG8_STAGE(PG8_SB(0, 0), b2, voffB); PG8_STAGE(PG8_SB(0, 1), b2 + hstep, voffB); PG8_STAGE(PG8_SA(0, 0), a2, voffA);
.LBB0_403:
	s_add_u32 s14, s8, 0xfffc0080
	s_addc_u32 s15, s9, -1
	s_add_i32 s16, 0, 0x10000
	s_cmp_eq_u32 s13, 12
	s_cselect_b32 s55, s2, s15
	s_cselect_b32 s54, s4, s14
	v_add_u32_e32 v128, s16, v149
	s_cselect_b32 s39, s5, s12
	s_cselect_b32 s38, s10, s11
	s_add_i32 s17, 0, 0x14000
	ds_read_b128 v[158:161], v128
	ds_read_b128 v[162:165], v128 offset:1024
	ds_read_b128 v[184:187], v128 offset:2048
	ds_read_b128 v[188:191], v128 offset:3072
	v_add_u32_e32 v128, s17, v149
	ds_read_b128 v[192:195], v128
	ds_read_b128 v[196:199], v128 offset:1024
	ds_read_b128 v[200:203], v128 offset:2048
	ds_read_b128 v[204:207], v128 offset:3072
	v_lshl_add_u64 v[166:167], s[8:9], 0, v[154:155]
	s_add_i32 m0, s59, 0xc000
	ds_read_b128 v[208:211], v147
	ds_read_b128 v[212:215], v147 offset:1024
	ds_read_b128 v[216:219], v147 offset:2048
	ds_read_b128 v[220:223], v147 offset:3072
	ds_read_b128 v[224:227], v147 offset:4096
	ds_read_b128 v[228:231], v147 offset:5120
	ds_read_b128 v[232:235], v147 offset:6144
	ds_read_b128 v[236:239], v147 offset:7168
	global_load_lds_dwordx4 v[166:167], off
	v_lshl_add_u64 v[166:167], s[8:9], 0, v[156:157]
	s_add_i32 m0, s59, 0xe000
	s_nop 0
	global_load_lds_dwordx4 v[166:167], off
	s_waitcnt vmcnt(8)
	s_waitcnt lgkmcnt(0)
	s_setprio 1
	s_barrier
	v_mfma_f32_16x16x32_bf16 v[124:127], v[158:161], v[208:211], v[124:127]
	v_mfma_f32_16x16x32_bf16 v[120:123], v[184:187], v[208:211], v[120:123]
	v_mfma_f32_16x16x32_bf16 v[108:111], v[158:161], v[216:219], v[108:111]
	v_mfma_f32_16x16x32_bf16 v[104:107], v[184:187], v[216:219], v[104:107]
	v_mfma_f32_16x16x32_bf16 v[92:95], v[158:161], v[224:227], v[92:95]
	v_mfma_f32_16x16x32_bf16 v[88:91], v[184:187], v[224:227], v[88:91]
	v_mfma_f32_16x16x32_bf16 v[76:79], v[158:161], v[232:235], v[76:79]
	v_mfma_f32_16x16x32_bf16 v[72:75], v[184:187], v[232:235], v[72:75]
	v_mfma_f32_16x16x32_bf16 v[124:127], v[162:165], v[212:215], v[124:127]
	v_mfma_f32_16x16x32_bf16 v[120:123], v[188:191], v[212:215], v[120:123]
	v_mfma_f32_16x16x32_bf16 v[108:111], v[162:165], v[220:223], v[108:111]
	v_mfma_f32_16x16x32_bf16 v[104:107], v[188:191], v[220:223], v[104:107]
	v_mfma_f32_16x16x32_bf16 v[92:95], v[162:165], v[228:231], v[92:95]
	v_mfma_f32_16x16x32_bf16 v[88:91], v[188:191], v[228:231], v[88:91]
	v_mfma_f32_16x16x32_bf16 v[76:79], v[162:165], v[236:239], v[76:79]
	v_mfma_f32_16x16x32_bf16 v[72:75], v[188:191], v[236:239], v[72:75]
	s_setprio 0
	s_setprio 1
	v_mfma_f32_16x16x32_bf16 v[116:119], v[192:195], v[208:211], v[116:119]
	v_mfma_f32_16x16x32_bf16 v[112:115], v[200:203], v[208:211], v[112:115]
	v_mfma_f32_16x16x32_bf16 v[100:103], v[192:195], v[216:219], v[100:103]
	v_mfma_f32_16x16x32_bf16 v[96:99], v[200:203], v[216:219], v[96:99]
	v_mfma_f32_16x16x32_bf16 v[84:87], v[192:195], v[224:227], v[84:87]
	v_mfma_f32_16x16x32_bf16 v[80:83], v[200:203], v[224:227], v[80:83]
	v_mfma_f32_16x16x32_bf16 v[68:71], v[192:195], v[232:235], v[68:71]
	v_mfma_f32_16x16x32_bf16 v[64:67], v[200:203], v[232:235], v[64:67]
	v_mfma_f32_16x16x32_bf16 v[116:119], v[196:199], v[212:215], v[116:119]
	v_mfma_f32_16x16x32_bf16 v[112:115], v[204:207], v[212:215], v[112:115]
	v_mfma_f32_16x16x32_bf16 v[100:103], v[196:199], v[220:223], v[100:103]
	v_mfma_f32_16x16x32_bf16 v[96:99], v[204:207], v[220:223], v[96:99]
	v_mfma_f32_16x16x32_bf16 v[84:87], v[196:199], v[228:231], v[84:87]
	v_mfma_f32_16x16x32_bf16 v[80:83], v[204:207], v[228:231], v[80:83]
	v_mfma_f32_16x16x32_bf16 v[68:71], v[196:199], v[236:239], v[68:71]
	v_mfma_f32_16x16x32_bf16 v[64:67], v[204:207], v[236:239], v[64:67]
	s_barrier
	s_setprio 0
	s_add_i32 s14, s16, s58
	v_lshl_add_u64 v[166:167], s[38:39], 0, v[140:141]
	s_mov_b32 m0, s14
	ds_read_b128 v[208:211], v147 offset:16384
	ds_read_b128 v[212:215], v147 offset:17408
	ds_read_b128 v[216:219], v147 offset:18432
	ds_read_b128 v[220:223], v147 offset:19456
	ds_read_b128 v[224:227], v147 offset:20480
	ds_read_b128 v[228:231], v147 offset:21504
	ds_read_b128 v[232:235], v147 offset:22528
	ds_read_b128 v[236:239], v147 offset:23552
	global_load_lds_dwordx4 v[166:167], off
	s_add_i32 m0, s14, 0x2000
	s_add_u32 s14, s38, 0x40000
	v_lshl_add_u64 v[180:181], s[38:39], 0, v[144:145]
	s_addc_u32 s15, s39, 0
	s_add_i32 s16, s17, s58
	global_load_lds_dwordx4 v[180:181], off
	v_lshl_add_u64 v[182:183], s[14:15], 0, v[140:141]
	s_mov_b32 m0, s16
	v_lshl_add_u64 v[240:241], s[54:55], 0, v[142:143]
	global_load_lds_dwordx4 v[182:183], off
	v_lshl_add_u64 v[182:183], s[14:15], 0, v[144:145]
	s_add_i32 m0, s16, 0x2000
	s_nop 0
	global_load_lds_dwordx4 v[182:183], off
	v_lshl_add_u64 v[182:183], s[54:55], 0, v[138:139]
	s_mov_b32 m0, s59
	s_nop 0
	global_load_lds_dwordx4 v[182:183], off
	s_mov_b32 m0, s60
	s_nop 0
	global_load_lds_dwordx4 v[240:241], off
	s_waitcnt vmcnt(8)
	s_waitcnt lgkmcnt(0)
	s_setprio 1
	s_barrier
; #define PG8_STAGE(bufoff, gbase, voff) do { _Pragma("unroll") for (int _i = 0; _i < 2; ++_i) \
;         __builtin_amdgcn_global_load_lds((const unsigned*)((const char*)(gbase) + (voff)[_i]), (LAS unsigned*)(lds + (bufoff) + ldsw + _i * 8192), 16, 0, 0); } while (0)
; #define PG8_LDA(dst, b, h) do { _Pragma("unroll") for (int m = 0; m < 4; ++m) _Pragma("unroll") for (int k = 0; k < 2; ++k) dst[m][k] = *(const LAS bf16x8*)(lds + PG8_SA(b, h) + aoff + m * 2048 + k * 1024); } while (0)
; #define PG8_LDB(dst, b, h) do { _Pragma("unroll") for (int n = 0; n < 2; ++n) _Pragma("unroll") for (int k = 0; k < 2; ++k) dst[n][k] = *(const LAS bf16x8*)(lds + PG8_SB(b, h) + boff + n * 2048 + k * 1024); } while (0)
; #define PG8_MMA(ai, bj, At, Bt) do { __builtin_amdgcn_s_setprio(1); _Pragma("unroll") for (int m = 0; m < 4; ++m) _Pragma("unroll") for (int n = 0; n < 2; ++n) _Pragma("unroll") for (int k = 0; k < 2; ++k) \
;         acc[ai][bj][m][n] = __builtin_amdgcn_mfma_f32_16x16x32_bf16(Bt[n][k], At[m][k], acc[ai][bj][m][n], 0, 0, 0); __builtin_amdgcn_s_setprio(0); } while (0)
; #define PG8_WAIT_V(n) asm volatile("s_waitcnt vmcnt(" #n ")" ::: "memory")
; #define PG8_WAIT_L(n) asm volatile("s_waitcnt lgkmcnt(" #n ")" ::: "memory")
; #define PG8_BAR __builtin_amdgcn_s_barrier()
; #define PG8_SCHED __builtin_amdgcn_sched_barrier(0)
; template <class Epi, class Sched>
; __device__ __forceinline__ void gemm_phase(LAS unsigned char* lds, const int K, const Sched& S, const Epi& E) {
;     ...
;             PG8_WAIT_V(8); PG8_WAIT_L(0); PG8_BAR; PG8_MMA(1, 0, At, B0); PG8_MMA(1, 1, At, B1); PG8_BAR; PG8_SCHED;
;             PG8_LDB(B0, 1, 0); PG8_LDB(B1, 1, 1); PG8_SCHED; PG8_LDA(At, 1, 0); PG8_STAGE(PG8_SA(0, 1), a2 + hstep, voffA);
;             PG8_WAIT_V(8); PG8_WAIT_L(0); PG8_BAR; PG8_MMA(0, 0, At, B0); PG8_MMA(0, 1, At, B1); PG8_BAR; PG8_SCHED;
	v_mfma_f32_16x16x32_bf16 v[60:63], v[158:161], v[208:211], v[60:63]
	v_mfma_f32_16x16x32_bf16 v[56:59], v[184:187], v[208:211], v[56:59]
	v_mfma_f32_16x16x32_bf16 v[44:47], v[158:161], v[216:219], v[44:47]
	v_mfma_f32_16x16x32_bf16 v[40:43], v[184:187], v[216:219], v[40:43]
	v_mfma_f32_16x16x32_bf16 v[28:31], v[158:161], v[224:227], v[28:31]
	v_mfma_f32_16x16x32_bf16 v[24:27], v[184:187], v[224:227], v[24:27]
	v_mfma_f32_16x16x32_bf16 v[12:15], v[158:161], v[232:235], v[12:15]
	v_mfma_f32_16x16x32_bf16 v[8:11], v[184:187], v[232:235], v[8:11]
	v_mfma_f32_16x16x32_bf16 v[60:63], v[162:165], v[212:215], v[60:63]
	v_mfma_f32_16x16x32_bf16 v[56:59], v[188:191], v[212:215], v[56:59]
	v_mfma_f32_16x16x32_bf16 v[44:47], v[162:165], v[220:223], v[44:47]
	v_mfma_f32_16x16x32_bf16 v[40:43], v[188:191], v[220:223], v[40:43]
	v_mfma_f32_16x16x32_bf16 v[28:31], v[162:165], v[228:231], v[28:31]
	v_mfma_f32_16x16x32_bf16 v[24:27], v[188:191], v[228:231], v[24:27]
	v_mfma_f32_16x16x32_bf16 v[12:15], v[162:165], v[236:239], v[12:15]
	v_mfma_f32_16x16x32_bf16 v[8:11], v[188:191], v[236:239], v[8:11]
	s_setprio 0
	s_setprio 1
	v_mfma_f32_16x16x32_bf16 v[52:55], v[192:195], v[208:211], v[52:55]
	v_mfma_f32_16x16x32_bf16 v[48:51], v[200:203], v[208:211], v[48:51]
	v_mfma_f32_16x16x32_bf16 v[36:39], v[192:195], v[216:219], v[36:39]
	v_mfma_f32_16x16x32_bf16 v[32:35], v[200:203], v[216:219], v[32:35]
	v_mfma_f32_16x16x32_bf16 v[20:23], v[192:195], v[224:227], v[20:23]
	v_mfma_f32_16x16x32_bf16 v[16:19], v[200:203], v[224:227], v[16:19]
	v_mfma_f32_16x16x32_bf16 v[4:7], v[192:195], v[232:235], v[4:7]
	v_mfma_f32_16x16x32_bf16 v[0:3], v[200:203], v[232:235], v[0:3]
	v_mfma_f32_16x16x32_bf16 v[52:55], v[196:199], v[212:215], v[52:55]
	v_mfma_f32_16x16x32_bf16 v[48:51], v[204:207], v[212:215], v[48:51]
	v_mfma_f32_16x16x32_bf16 v[36:39], v[196:199], v[220:223], v[36:39]
	v_mfma_f32_16x16x32_bf16 v[32:35], v[204:207], v[220:223], v[32:35]
	v_mfma_f32_16x16x32_bf16 v[20:23], v[196:199], v[228:231], v[20:23]
	v_mfma_f32_16x16x32_bf16 v[16:19], v[204:207], v[228:231], v[16:19]
	v_mfma_f32_16x16x32_bf16 v[4:7], v[196:199], v[236:239], v[4:7]
	v_mfma_f32_16x16x32_bf16 v[0:3], v[204:207], v[236:239], v[0:3]
	s_barrier
	s_setprio 0
	s_add_i32 s16, 0, 0x18000
	v_add_u32_e32 v128, s16, v149
	s_add_i32 s17, 0, 0x1c000
	ds_read_b128 v[158:161], v128
	ds_read_b128 v[162:165], v128 offset:1024
	ds_read_b128 v[184:187], v128 offset:2048
	ds_read_b128 v[188:191], v128 offset:3072
	v_add_u32_e32 v128, s17, v149
	ds_read_b128 v[192:195], v128
	ds_read_b128 v[196:199], v128 offset:1024
	ds_read_b128 v[200:203], v128 offset:2048
	ds_read_b128 v[204:207], v128 offset:3072
	s_add_u32 s14, s54, 0x40000
	s_addc_u32 s15, s55, 0
	s_mov_b32 m0, s61
	v_lshl_add_u64 v[242:243], s[14:15], 0, v[138:139]
	ds_read_b128 v[208:211], v147 offset:32768
	ds_read_b128 v[212:215], v147 offset:33792
	ds_read_b128 v[216:219], v147 offset:34816
	ds_read_b128 v[220:223], v147 offset:35840
	ds_read_b128 v[224:227], v147 offset:36864
	ds_read_b128 v[228:231], v147 offset:37888
	ds_read_b128 v[232:235], v147 offset:38912
	ds_read_b128 v[236:239], v147 offset:39936
	global_load_lds_dwordx4 v[242:243], off
	v_lshl_add_u64 v[242:243], s[14:15], 0, v[142:143]
	s_mov_b32 m0, s62
	s_nop 0
	global_load_lds_dwordx4 v[242:243], off
	s_waitcnt vmcnt(8)
	s_waitcnt lgkmcnt(0)
	s_setprio 1
	s_barrier
	v_mfma_f32_16x16x32_bf16 v[124:127], v[158:161], v[208:211], v[124:127]
	v_mfma_f32_16x16x32_bf16 v[120:123], v[184:187], v[208:211], v[120:123]
	v_mfma_f32_16x16x32_bf16 v[108:111], v[158:161], v[216:219], v[108:111]
	v_mfma_f32_16x16x32_bf16 v[104:107], v[184:187], v[216:219], v[104:107]
	v_mfma_f32_16x16x32_bf16 v[92:95], v[158:161], v[224:227], v[92:95]
	v_mfma_f32_16x16x32_bf16 v[88:91], v[184:187], v[224:227], v[88:91]
	v_mfma_f32_16x16x32_bf16 v[76:79], v[158:161], v[232:235], v[76:79]
	v_mfma_f32_16x16x32_bf16 v[72:75], v[184:187], v[232:235], v[72:75]
	v_mfma_f32_16x16x32_bf16 v[124:127], v[162:165], v[212:215], v[124:127]
	v_mfma_f32_16x16x32_bf16 v[120:123], v[188:191], v[212:215], v[120:123]
	v_mfma_f32_16x16x32_bf16 v[108:111], v[162:165], v[220:223], v[108:111]
	v_mfma_f32_16x16x32_bf16 v[104:107], v[188:191], v[220:223], v[104:107]
	v_mfma_f32_16x16x32_bf16 v[92:95], v[162:165], v[228:231], v[92:95]
	v_mfma_f32_16x16x32_bf16 v[88:91], v[188:191], v[228:231], v[88:91]
	v_mfma_f32_16x16x32_bf16 v[76:79], v[162:165], v[236:239], v[76:79]
	v_mfma_f32_16x16x32_bf16 v[72:75], v[188:191], v[236:239], v[72:75]
	s_setprio 0
	s_setprio 1
	v_mfma_f32_16x16x32_bf16 v[116:119], v[192:195], v[208:211], v[116:119]
	v_mfma_f32_16x16x32_bf16 v[112:115], v[200:203], v[208:211], v[112:115]
	v_mfma_f32_16x16x32_bf16 v[100:103], v[192:195], v[216:219], v[100:103]
	v_mfma_f32_16x16x32_bf16 v[96:99], v[200:203], v[216:219], v[96:99]
	v_mfma_f32_16x16x32_bf16 v[84:87], v[192:195], v[224:227], v[84:87]
	v_mfma_f32_16x16x32_bf16 v[80:83], v[200:203], v[224:227], v[80:83]
	v_mfma_f32_16x16x32_bf16 v[68:71], v[192:195], v[232:235], v[68:71]
	v_mfma_f32_16x16x32_bf16 v[64:67], v[200:203], v[232:235], v[64:67]
	v_mfma_f32_16x16x32_bf16 v[116:119], v[196:199], v[212:215], v[116:119]
	v_mfma_f32_16x16x32_bf16 v[112:115], v[204:207], v[212:215], v[112:115]
	v_mfma_f32_16x16x32_bf16 v[100:103], v[196:199], v[220:223], v[100:103]
	v_mfma_f32_16x16x32_bf16 v[96:99], v[204:207], v[220:223], v[96:99]
	v_mfma_f32_16x16x32_bf16 v[84:87], v[196:199], v[228:231], v[84:87]
	v_mfma_f32_16x16x32_bf16 v[80:83], v[204:207], v[228:231], v[80:83]
	v_mfma_f32_16x16x32_bf16 v[68:71], v[196:199], v[236:239], v[68:71]
	v_mfma_f32_16x16x32_bf16 v[64:67], v[204:207], v[236:239], v[64:67]
	s_barrier
; #define PG8_STAGE(bufoff, gbase, voff) do { _Pragma("unroll") for (int _i = 0; _i < 2; ++_i) \
;         __builtin_amdgcn_global_load_lds((const unsigned*)((const char*)(gbase) + (voff)[_i]), (LAS unsigned*)(lds + (bufoff) + ldsw + _i * 8192), 16, 0, 0); } while (0)
; #define PG8_LDA(dst, b, h) do { _Pragma("unroll") for (int m = 0; m < 4; ++m) _Pragma("unroll") for (int k = 0; k < 2; ++k) dst[m][k] = *(const LAS bf16x8*)(lds + PG8_SA(b, h) + aoff + m * 2048 + k * 1024); } while (0)
; #define PG8_MMA(ai, bj, At, Bt) do { __builtin_amdgcn_s_setprio(1); _Pragma("unroll") for (int m = 0; m < 4; ++m) _Pragma("unroll") for (int n = 0; n < 2; ++n) _Pragma("unroll") for (int k = 0; k < 2; ++k) \
;         acc[ai][bj][m][n] = __builtin_amdgcn_mfma_f32_16x16x32_bf16(Bt[n][k], At[m][k], acc[ai][bj][m][n], 0, 0, 0); __builtin_amdgcn_s_setprio(0); } while (0)
; #define PG8_WAIT_V(n) asm volatile("s_waitcnt vmcnt(" #n ")" ::: "memory")
; #define PG8_WAIT_L(n) asm volatile("s_waitcnt lgkmcnt(" #n ")" ::: "memory")
; #define PG8_BAR __builtin_amdgcn_s_barrier()
; #define PG8_SCHED __builtin_amdgcn_sched_barrier(0)
; template <class Epi, class Sched>
; __device__ __forceinline__ void gemm_phase(LAS unsigned char* lds, const int K, const Sched& S, const Epi& E) {
;     ...
;             PG8_LDA(At, 1, 1); PG8_STAGE(PG8_SB(1, 0), b3, voffB); PG8_STAGE(PG8_SB(1, 1), b3 + hstep, voffB); PG8_STAGE(PG8_SA(1, 0), a3, voffA);
;             PG8_WAIT_V(8); PG8_WAIT_L(0); PG8_BAR; PG8_MMA(1, 0, At, B0); PG8_MMA(1, 1, At, B1); PG8_BAR; PG8_SCHED;
;         }
;         if (wr == 0) PG8_BAR;
	s_setprio 0
	s_add_i32 s14, s16, s58
	v_lshl_add_u64 v[166:167], v[166:167], 0, s[36:37]
	s_mov_b32 m0, s14
	ds_read_b128 v[208:211], v147 offset:49152
	ds_read_b128 v[212:215], v147 offset:50176
	ds_read_b128 v[216:219], v147 offset:51200
	ds_read_b128 v[220:223], v147 offset:52224
	ds_read_b128 v[224:227], v147 offset:53248
	ds_read_b128 v[228:231], v147 offset:54272
	ds_read_b128 v[232:235], v147 offset:55296
	ds_read_b128 v[236:239], v147 offset:56320
	global_load_lds_dwordx4 v[166:167], off
	s_add_i32 m0, s14, 0x2000
	s_add_u32 s14, s38, 0x40080
	v_lshl_add_u64 v[166:167], v[180:181], 0, s[36:37]
	s_addc_u32 s15, s39, 0
	s_add_i32 s16, s17, s58
	global_load_lds_dwordx4 v[166:167], off
	v_lshl_add_u64 v[166:167], s[14:15], 0, v[140:141]
	s_mov_b32 m0, s16
	s_nop 0
	global_load_lds_dwordx4 v[166:167], off
	v_lshl_add_u64 v[166:167], s[14:15], 0, v[144:145]
	s_add_i32 m0, s16, 0x2000
	s_nop 0
	global_load_lds_dwordx4 v[166:167], off
	v_lshl_add_u64 v[166:167], v[182:183], 0, s[36:37]
	s_mov_b32 m0, s64
	s_nop 0
	global_load_lds_dwordx4 v[166:167], off
	v_lshl_add_u64 v[166:167], v[240:241], 0, s[36:37]
	s_mov_b32 m0, s65
	s_nop 0
	global_load_lds_dwordx4 v[166:167], off
	s_waitcnt vmcnt(8)
	s_waitcnt lgkmcnt(0)
	s_setprio 1
	s_barrier
	v_mfma_f32_16x16x32_bf16 v[60:63], v[158:161], v[208:211], v[60:63]
	v_mfma_f32_16x16x32_bf16 v[56:59], v[184:187], v[208:211], v[56:59]
	v_mfma_f32_16x16x32_bf16 v[44:47], v[158:161], v[216:219], v[44:47]
	v_mfma_f32_16x16x32_bf16 v[40:43], v[184:187], v[216:219], v[40:43]
	v_mfma_f32_16x16x32_bf16 v[28:31], v[158:161], v[224:227], v[28:31]
	v_mfma_f32_16x16x32_bf16 v[24:27], v[184:187], v[224:227], v[24:27]
	v_mfma_f32_16x16x32_bf16 v[12:15], v[158:161], v[232:235], v[12:15]
	v_mfma_f32_16x16x32_bf16 v[8:11], v[184:187], v[232:235], v[8:11]
	v_mfma_f32_16x16x32_bf16 v[60:63], v[162:165], v[212:215], v[60:63]
	v_mfma_f32_16x16x32_bf16 v[56:59], v[188:191], v[212:215], v[56:59]
	v_mfma_f32_16x16x32_bf16 v[44:47], v[162:165], v[220:223], v[44:47]
	v_mfma_f32_16x16x32_bf16 v[40:43], v[188:191], v[220:223], v[40:43]
	v_mfma_f32_16x16x32_bf16 v[28:31], v[162:165], v[228:231], v[28:31]
	v_mfma_f32_16x16x32_bf16 v[24:27], v[188:191], v[228:231], v[24:27]
	v_mfma_f32_16x16x32_bf16 v[12:15], v[162:165], v[236:239], v[12:15]
	v_mfma_f32_16x16x32_bf16 v[8:11], v[188:191], v[236:239], v[8:11]
	s_setprio 0
	s_setprio 1
	v_mfma_f32_16x16x32_bf16 v[52:55], v[192:195], v[208:211], v[52:55]
	v_mfma_f32_16x16x32_bf16 v[48:51], v[200:203], v[208:211], v[48:51]
	v_mfma_f32_16x16x32_bf16 v[36:39], v[192:195], v[216:219], v[36:39]
	v_mfma_f32_16x16x32_bf16 v[32:35], v[200:203], v[216:219], v[32:35]
	v_mfma_f32_16x16x32_bf16 v[20:23], v[192:195], v[224:227], v[20:23]
	v_mfma_f32_16x16x32_bf16 v[16:19], v[200:203], v[224:227], v[16:19]
	v_mfma_f32_16x16x32_bf16 v[4:7], v[192:195], v[232:235], v[4:7]
	v_mfma_f32_16x16x32_bf16 v[0:3], v[200:203], v[232:235], v[0:3]
	v_mfma_f32_16x16x32_bf16 v[52:55], v[196:199], v[212:215], v[52:55]
	v_mfma_f32_16x16x32_bf16 v[48:51], v[204:207], v[212:215], v[48:51]
	v_mfma_f32_16x16x32_bf16 v[36:39], v[196:199], v[220:223], v[36:39]
	v_mfma_f32_16x16x32_bf16 v[32:35], v[204:207], v[220:223], v[32:35]
	v_mfma_f32_16x16x32_bf16 v[20:23], v[196:199], v[228:231], v[20:23]
	v_mfma_f32_16x16x32_bf16 v[16:19], v[204:207], v[228:231], v[16:19]
	v_mfma_f32_16x16x32_bf16 v[4:7], v[196:199], v[236:239], v[4:7]
	v_mfma_f32_16x16x32_bf16 v[0:3], v[204:207], v[236:239], v[0:3]
	s_barrier
	s_setprio 0
	s_add_i32 s13, s13, 2
	s_add_u32 s8, s8, 0x100
	s_addc_u32 s9, s9, 0
	s_add_u32 s11, s11, 0x100
	s_addc_u32 s12, s12, 0
	s_cmp_gt_u32 s13, 13
	s_cbranch_scc0 .LBB0_403
	s_and_b64 vcc, exec, s[42:43]
	s_cbranch_vccz .LBB0_406
	s_barrier

; #define PG8_STAGE(bufoff, gbase, voff) do { _Pragma("unroll") for (int _i = 0; _i < 2; ++_i) \
;         __builtin_amdgcn_global_load_lds((const unsigned*)((const char*)(gbase) + (voff)[_i]), (LAS unsigned*)(lds + (bufoff) + ldsw + _i * 8192), 16, 0, 0); } while (0)
; #define PG8_LDA(dst, b, h) do { _Pragma("unroll") for (int m = 0; m < 4; ++m) _Pragma("unroll") for (int k = 0; k < 2; ++k) dst[m][k] = *(const LAS bf16x8*)(lds + PG8_SA(b, h) + aoff + m * 2048 + k * 1024); } while (0)
; #define PG8_LDB(dst, b, h) do { _Pragma("unroll") for (int n = 0; n < 2; ++n) _Pragma("unroll") for (int k = 0; k < 2; ++k) dst[n][k] = *(const LAS bf16x8*)(lds + PG8_SB(b, h) + boff + n * 2048 + k * 1024); } while (0)
; #define PG8_MMA(ai, bj, At, Bt) do { __builtin_amdgcn_s_setprio(1); _Pragma("unroll") for (int m = 0; m < 4; ++m) _Pragma("unroll") for (int n = 0; n < 2; ++n) _Pragma("unroll") for (int k = 0; k < 2; ++k) \
;         acc[ai][bj][m][n] = __builtin_amdgcn_mfma_f32_16x16x32_bf16(Bt[n][k], At[m][k], acc[ai][bj][m][n], 0, 0, 0); __builtin_amdgcn_s_setprio(0); } while (0)
; #define PG8_WAIT_V(n) asm volatile("s_waitcnt vmcnt(" #n ")" ::: "memory")
; #define PG8_WAIT_L(n) asm volatile("s_waitcnt lgkmcnt(" #n ")" ::: "memory")
; #define PG8_BAR __builtin_amdgcn_s_barrier()
; #define PG8_SCHED __builtin_amdgcn_sched_barrier(0)
; template <class Epi, class Sched>
; __device__ __forceinline__ void gemm_phase(LAS unsigned char* lds, const int K, const Sched& S, const Epi& E) {
;     ...
;             const bool last = (t == nt - 2);
;             const char* a1 = cA + (size_t)(t + 1) * kstep;
;             const char* a2 = last ? nA : cA + (size_t)(t + 2) * kstep; const char* b2 = last ? nB : cB + (size_t)(t + 2) * kstep;
;             const char* a3 = a2 + kstep; const char* b3 = b2 + kstep;
;             PG8_LDB(B0, 0, 0); PG8_LDB(B1, 0, 1); PG8_SCHED; PG8_LDA(At, 0, 0); PG8_STAGE(PG8_SA(1, 1), a1 + hstep, voffA);
;             PG8_WAIT_V(8); PG8_WAIT_L(0); PG8_BAR; PG8_MMA(0, 0, At, B0); PG8_MMA(0, 1, At, B1); PG8_BAR; PG8_SCHED;
;             PG8_LDA(At, 0, 1); PG8_STAGE(PG8_SB(0, 0), b2, voffB); PG8_STAGE(PG8_SB(0, 1), b2 + hstep, voffB); PG8_STAGE(PG8_SA(0, 0), a2, voffA);
.LBB0_511:
	s_add_i32 s14, s8, 0xfaf9e080
	s_cmp_lg_u32 s13, 60
	s_cselect_b32 s14, s14, 0
	s_add_u32 s40, s28, s14
	s_addc_u32 s41, s29, 0
	s_add_i32 s15, 0, 0x10000
	s_add_u32 s38, s34, s14
	s_addc_u32 s39, s35, 0
	s_add_i32 s16, 0, 0x14000
	v_add_u32_e32 v164, s15, v145
	v_add_u32_e32 v180, s16, v145
	ds_read_b128 v[152:155], v164
	ds_read_b128 v[156:159], v164 offset:1024
	ds_read_b128 v[160:163], v164 offset:2048
	ds_read_b128 v[164:167], v164 offset:3072
	ds_read_b128 v[184:187], v180
	ds_read_b128 v[188:191], v180 offset:1024
	ds_read_b128 v[192:195], v180 offset:2048
	ds_read_b128 v[196:199], v180 offset:3072
	v_lshl_add_u64 v[180:181], v[146:147], 0, s[8:9]
	s_add_i32 m0, s2, 0xc000
	ds_read_b128 v[200:203], v151
	ds_read_b128 v[204:207], v151 offset:1024
	ds_read_b128 v[208:211], v151 offset:2048
	ds_read_b128 v[212:215], v151 offset:3072
	ds_read_b128 v[216:219], v151 offset:4096
	ds_read_b128 v[220:223], v151 offset:5120
	ds_read_b128 v[224:227], v151 offset:6144
	ds_read_b128 v[228:231], v151 offset:7168
	global_load_lds_dwordx4 v[180:181], off
	v_lshl_add_u64 v[180:181], v[148:149], 0, s[8:9]
	s_add_i32 m0, s2, 0xe000
	s_nop 0
	global_load_lds_dwordx4 v[180:181], off
	s_waitcnt vmcnt(8)
	s_waitcnt lgkmcnt(0)
	s_setprio 1
	s_barrier
	v_mfma_f32_16x16x32_bf16 v[124:127], v[152:155], v[200:203], v[124:127]
	v_mfma_f32_16x16x32_bf16 v[120:123], v[160:163], v[200:203], v[120:123]
	v_mfma_f32_16x16x32_bf16 v[108:111], v[152:155], v[208:211], v[108:111]
	v_mfma_f32_16x16x32_bf16 v[104:107], v[160:163], v[208:211], v[104:107]
	v_mfma_f32_16x16x32_bf16 v[92:95], v[152:155], v[216:219], v[92:95]
	v_mfma_f32_16x16x32_bf16 v[88:91], v[160:163], v[216:219], v[88:91]
	v_mfma_f32_16x16x32_bf16 v[76:79], v[152:155], v[224:227], v[76:79]
	v_mfma_f32_16x16x32_bf16 v[72:75], v[160:163], v[224:227], v[72:75]
	v_mfma_f32_16x16x32_bf16 v[124:127], v[156:159], v[204:207], v[124:127]
	v_mfma_f32_16x16x32_bf16 v[120:123], v[164:167], v[204:207], v[120:123]
	v_mfma_f32_16x16x32_bf16 v[108:111], v[156:159], v[212:215], v[108:111]
	v_mfma_f32_16x16x32_bf16 v[104:107], v[164:167], v[212:215], v[104:107]
	v_mfma_f32_16x16x32_bf16 v[92:95], v[156:159], v[220:223], v[92:95]
	v_mfma_f32_16x16x32_bf16 v[88:91], v[164:167], v[220:223], v[88:91]
	v_mfma_f32_16x16x32_bf16 v[76:79], v[156:159], v[228:231], v[76:79]
	v_mfma_f32_16x16x32_bf16 v[72:75], v[164:167], v[228:231], v[72:75]
	s_setprio 0
	s_setprio 1
	v_mfma_f32_16x16x32_bf16 v[116:119], v[184:187], v[200:203], v[116:119]
	v_mfma_f32_16x16x32_bf16 v[112:115], v[192:195], v[200:203], v[112:115]
	v_mfma_f32_16x16x32_bf16 v[100:103], v[184:187], v[208:211], v[100:103]
	v_mfma_f32_16x16x32_bf16 v[96:99], v[192:195], v[208:211], v[96:99]
	v_mfma_f32_16x16x32_bf16 v[84:87], v[184:187], v[216:219], v[84:87]
	v_mfma_f32_16x16x32_bf16 v[80:83], v[192:195], v[216:219], v[80:83]
	v_mfma_f32_16x16x32_bf16 v[68:71], v[184:187], v[224:227], v[68:71]
	v_mfma_f32_16x16x32_bf16 v[64:67], v[192:195], v[224:227], v[64:67]
	v_mfma_f32_16x16x32_bf16 v[116:119], v[188:191], v[204:207], v[116:119]
	v_mfma_f32_16x16x32_bf16 v[112:115], v[196:199], v[204:207], v[112:115]
	v_mfma_f32_16x16x32_bf16 v[100:103], v[188:191], v[212:215], v[100:103]
	v_mfma_f32_16x16x32_bf16 v[96:99], v[196:199], v[212:215], v[96:99]
	v_mfma_f32_16x16x32_bf16 v[84:87], v[188:191], v[220:223], v[84:87]
	v_mfma_f32_16x16x32_bf16 v[80:83], v[196:199], v[220:223], v[80:83]
	v_mfma_f32_16x16x32_bf16 v[68:71], v[188:191], v[228:231], v[68:71]
	v_mfma_f32_16x16x32_bf16 v[64:67], v[196:199], v[228:231], v[64:67]
	s_barrier
	s_setprio 0
	s_add_i32 s14, s15, s1
	v_lshl_add_u64 v[180:181], s[38:39], 0, v[128:129]
	s_mov_b32 m0, s14
	ds_read_b128 v[200:203], v151 offset:16384
	ds_read_b128 v[204:207], v151 offset:17408
	ds_read_b128 v[208:211], v151 offset:18432
	ds_read_b128 v[212:215], v151 offset:19456
	ds_read_b128 v[216:219], v151 offset:20480
	ds_read_b128 v[220:223], v151 offset:21504
	ds_read_b128 v[224:227], v151 offset:22528
	ds_read_b128 v[228:231], v151 offset:23552
	global_load_lds_dwordx4 v[180:181], off
	s_add_i32 m0, s14, 0x2000
	s_add_u32 s14, s38, 0x100000
	v_lshl_add_u64 v[182:183], s[38:39], 0, v[138:139]
	s_addc_u32 s15, s39, 0
	s_add_i32 s16, s16, s1
	global_load_lds_dwordx4 v[182:183], off
	v_lshl_add_u64 v[232:233], s[14:15], 0, v[128:129]
	s_mov_b32 m0, s16
	v_lshl_add_u64 v[234:235], s[40:41], 0, v[140:141]
	global_load_lds_dwordx4 v[232:233], off
	v_lshl_add_u64 v[232:233], s[14:15], 0, v[138:139]
	s_add_i32 m0, s16, 0x2000
	s_nop 0
	global_load_lds_dwordx4 v[232:233], off
	v_lshl_add_u64 v[232:233], s[40:41], 0, v[142:143]
	s_mov_b32 m0, s2
	s_nop 0
	global_load_lds_dwordx4 v[232:233], off
	s_mov_b32 m0, s3
	s_nop 0
	global_load_lds_dwordx4 v[234:235], off
	s_waitcnt vmcnt(8)
	s_waitcnt lgkmcnt(0)
	s_setprio 1
	s_barrier
; #define PG8_STAGE(bufoff, gbase, voff) do { _Pragma("unroll") for (int _i = 0; _i < 2; ++_i) \
;         __builtin_amdgcn_global_load_lds((const unsigned*)((const char*)(gbase) + (voff)[_i]), (LAS unsigned*)(lds + (bufoff) + ldsw + _i * 8192), 16, 0, 0); } while (0)
; #define PG8_LDA(dst, b, h) do { _Pragma("unroll") for (int m = 0; m < 4; ++m) _Pragma("unroll") for (int k = 0; k < 2; ++k) dst[m][k] = *(const LAS bf16x8*)(lds + PG8_SA(b, h) + aoff + m * 2048 + k * 1024); } while (0)
; #define PG8_LDB(dst, b, h) do { _Pragma("unroll") for (int n = 0; n < 2; ++n) _Pragma("unroll") for (int k = 0; k < 2; ++k) dst[n][k] = *(const LAS bf16x8*)(lds + PG8_SB(b, h) + boff + n * 2048 + k * 1024); } while (0)
; #define PG8_MMA(ai, bj, At, Bt) do { __builtin_amdgcn_s_setprio(1); _Pragma("unroll") for (int m = 0; m < 4; ++m) _Pragma("unroll") for (int n = 0; n < 2; ++n) _Pragma("unroll") for (int k = 0; k < 2; ++k) \
;         acc[ai][bj][m][n] = __builtin_amdgcn_mfma_f32_16x16x32_bf16(Bt[n][k], At[m][k], acc[ai][bj][m][n], 0, 0, 0); __builtin_amdgcn_s_setprio(0); } while (0)
; #define PG8_WAIT_V(n) asm volatile("s_waitcnt vmcnt(" #n ")" ::: "memory")
; #define PG8_WAIT_L(n) asm volatile("s_waitcnt lgkmcnt(" #n ")" ::: "memory")
; #define PG8_BAR __builtin_amdgcn_s_barrier()
; #define PG8_SCHED __builtin_amdgcn_sched_barrier(0)
; template <class Epi, class Sched>
; __device__ __forceinline__ void gemm_phase(LAS unsigned char* lds, const int K, const Sched& S, const Epi& E) {
;     ...
;             PG8_WAIT_V(8); PG8_WAIT_L(0); PG8_BAR; PG8_MMA(1, 0, At, B0); PG8_MMA(1, 1, At, B1); PG8_BAR; PG8_SCHED;
;             PG8_LDB(B0, 1, 0); PG8_LDB(B1, 1, 1); PG8_SCHED; PG8_LDA(At, 1, 0); PG8_STAGE(PG8_SA(0, 1), a2 + hstep, voffA);
;             PG8_WAIT_V(8); PG8_WAIT_L(0); PG8_BAR; PG8_MMA(0, 0, At, B0); PG8_MMA(0, 1, At, B1); PG8_BAR; PG8_SCHED;
	v_mfma_f32_16x16x32_bf16 v[60:63], v[152:155], v[200:203], v[60:63]
	v_mfma_f32_16x16x32_bf16 v[56:59], v[160:163], v[200:203], v[56:59]
	v_mfma_f32_16x16x32_bf16 v[44:47], v[152:155], v[208:211], v[44:47]
	v_mfma_f32_16x16x32_bf16 v[40:43], v[160:163], v[208:211], v[40:43]
	v_mfma_f32_16x16x32_bf16 v[28:31], v[152:155], v[216:219], v[28:31]
	v_mfma_f32_16x16x32_bf16 v[24:27], v[160:163], v[216:219], v[24:27]
	v_mfma_f32_16x16x32_bf16 v[12:15], v[152:155], v[224:227], v[12:15]
	v_mfma_f32_16x16x32_bf16 v[8:11], v[160:163], v[224:227], v[8:11]
	v_mfma_f32_16x16x32_bf16 v[60:63], v[156:159], v[204:207], v[60:63]
	v_mfma_f32_16x16x32_bf16 v[56:59], v[164:167], v[204:207], v[56:59]
	v_mfma_f32_16x16x32_bf16 v[44:47], v[156:159], v[212:215], v[44:47]
	v_mfma_f32_16x16x32_bf16 v[40:43], v[164:167], v[212:215], v[40:43]
	v_mfma_f32_16x16x32_bf16 v[28:31], v[156:159], v[220:223], v[28:31]
	v_mfma_f32_16x16x32_bf16 v[24:27], v[164:167], v[220:223], v[24:27]
	v_mfma_f32_16x16x32_bf16 v[12:15], v[156:159], v[228:231], v[12:15]
	v_mfma_f32_16x16x32_bf16 v[8:11], v[164:167], v[228:231], v[8:11]
	s_setprio 0
	s_setprio 1
	v_mfma_f32_16x16x32_bf16 v[52:55], v[184:187], v[200:203], v[52:55]
	v_mfma_f32_16x16x32_bf16 v[48:51], v[192:195], v[200:203], v[48:51]
	v_mfma_f32_16x16x32_bf16 v[36:39], v[184:187], v[208:211], v[36:39]
	v_mfma_f32_16x16x32_bf16 v[32:35], v[192:195], v[208:211], v[32:35]
	v_mfma_f32_16x16x32_bf16 v[20:23], v[184:187], v[216:219], v[20:23]
	v_mfma_f32_16x16x32_bf16 v[16:19], v[192:195], v[216:219], v[16:19]
	v_mfma_f32_16x16x32_bf16 v[4:7], v[184:187], v[224:227], v[4:7]
	v_mfma_f32_16x16x32_bf16 v[0:3], v[192:195], v[224:227], v[0:3]
	v_mfma_f32_16x16x32_bf16 v[52:55], v[188:191], v[204:207], v[52:55]
	v_mfma_f32_16x16x32_bf16 v[48:51], v[196:199], v[204:207], v[48:51]
	v_mfma_f32_16x16x32_bf16 v[36:39], v[188:191], v[212:215], v[36:39]
	v_mfma_f32_16x16x32_bf16 v[32:35], v[196:199], v[212:215], v[32:35]
	v_mfma_f32_16x16x32_bf16 v[20:23], v[188:191], v[220:223], v[20:23]
	v_mfma_f32_16x16x32_bf16 v[16:19], v[196:199], v[220:223], v[16:19]
	v_mfma_f32_16x16x32_bf16 v[4:7], v[188:191], v[228:231], v[4:7]
	v_mfma_f32_16x16x32_bf16 v[0:3], v[196:199], v[228:231], v[0:3]
	s_barrier
	s_setprio 0
	s_add_i32 s16, 0, 0x18000
	s_add_i32 s17, 0, 0x1c000
	v_add_u32_e32 v164, s16, v145
	v_add_u32_e32 v196, s17, v145
	ds_read_b128 v[152:155], v164
	ds_read_b128 v[156:159], v164 offset:1024
	ds_read_b128 v[160:163], v164 offset:2048
	ds_read_b128 v[164:167], v164 offset:3072
	ds_read_b128 v[184:187], v196
	ds_read_b128 v[188:191], v196 offset:1024
	ds_read_b128 v[192:195], v196 offset:2048
	ds_read_b128 v[196:199], v196 offset:3072
	s_add_u32 s14, s40, 0x100000
	s_addc_u32 s15, s41, 0
	s_mov_b32 m0, s4
	v_lshl_add_u64 v[236:237], s[14:15], 0, v[142:143]
	ds_read_b128 v[200:203], v151 offset:32768
	ds_read_b128 v[204:207], v151 offset:33792
	ds_read_b128 v[208:211], v151 offset:34816
	ds_read_b128 v[212:215], v151 offset:35840
	ds_read_b128 v[216:219], v151 offset:36864
	ds_read_b128 v[220:223], v151 offset:37888
	ds_read_b128 v[224:227], v151 offset:38912
	ds_read_b128 v[228:231], v151 offset:39936
	global_load_lds_dwordx4 v[236:237], off
	v_lshl_add_u64 v[236:237], s[14:15], 0, v[140:141]
	s_mov_b32 m0, s5
	s_nop 0
	global_load_lds_dwordx4 v[236:237], off
	s_waitcnt vmcnt(8)
	s_waitcnt lgkmcnt(0)
	s_setprio 1
	s_barrier
	v_mfma_f32_16x16x32_bf16 v[124:127], v[152:155], v[200:203], v[124:127]
	v_mfma_f32_16x16x32_bf16 v[120:123], v[160:163], v[200:203], v[120:123]
	v_mfma_f32_16x16x32_bf16 v[108:111], v[152:155], v[208:211], v[108:111]
	v_mfma_f32_16x16x32_bf16 v[104:107], v[160:163], v[208:211], v[104:107]
	v_mfma_f32_16x16x32_bf16 v[92:95], v[152:155], v[216:219], v[92:95]
	v_mfma_f32_16x16x32_bf16 v[88:91], v[160:163], v[216:219], v[88:91]
	v_mfma_f32_16x16x32_bf16 v[76:79], v[152:155], v[224:227], v[76:79]
	v_mfma_f32_16x16x32_bf16 v[72:75], v[160:163], v[224:227], v[72:75]
	v_mfma_f32_16x16x32_bf16 v[124:127], v[156:159], v[204:207], v[124:127]
	v_mfma_f32_16x16x32_bf16 v[120:123], v[164:167], v[204:207], v[120:123]
	v_mfma_f32_16x16x32_bf16 v[108:111], v[156:159], v[212:215], v[108:111]
	v_mfma_f32_16x16x32_bf16 v[104:107], v[164:167], v[212:215], v[104:107]
	v_mfma_f32_16x16x32_bf16 v[92:95], v[156:159], v[220:223], v[92:95]
	v_mfma_f32_16x16x32_bf16 v[88:91], v[164:167], v[220:223], v[88:91]
	v_mfma_f32_16x16x32_bf16 v[76:79], v[156:159], v[228:231], v[76:79]
	v_mfma_f32_16x16x32_bf16 v[72:75], v[164:167], v[228:231], v[72:75]
	s_setprio 0
	s_setprio 1
	v_mfma_f32_16x16x32_bf16 v[116:119], v[184:187], v[200:203], v[116:119]
	v_mfma_f32_16x16x32_bf16 v[112:115], v[192:195], v[200:203], v[112:115]
	v_mfma_f32_16x16x32_bf16 v[100:103], v[184:187], v[208:211], v[100:103]
	v_mfma_f32_16x16x32_bf16 v[96:99], v[192:195], v[208:211], v[96:99]
	v_mfma_f32_16x16x32_bf16 v[84:87], v[184:187], v[216:219], v[84:87]
	v_mfma_f32_16x16x32_bf16 v[80:83], v[192:195], v[216:219], v[80:83]
	v_mfma_f32_16x16x32_bf16 v[68:71], v[184:187], v[224:227], v[68:71]
	v_mfma_f32_16x16x32_bf16 v[64:67], v[192:195], v[224:227], v[64:67]
	v_mfma_f32_16x16x32_bf16 v[116:119], v[188:191], v[204:207], v[116:119]
	v_mfma_f32_16x16x32_bf16 v[112:115], v[196:199], v[204:207], v[112:115]
	v_mfma_f32_16x16x32_bf16 v[100:103], v[188:191], v[212:215], v[100:103]
	v_mfma_f32_16x16x32_bf16 v[96:99], v[196:199], v[212:215], v[96:99]
	v_mfma_f32_16x16x32_bf16 v[84:87], v[188:191], v[220:223], v[84:87]
	v_mfma_f32_16x16x32_bf16 v[80:83], v[196:199], v[220:223], v[80:83]
	v_mfma_f32_16x16x32_bf16 v[68:71], v[188:191], v[228:231], v[68:71]
	v_mfma_f32_16x16x32_bf16 v[64:67], v[196:199], v[228:231], v[64:67]
	s_barrier
; #define PG8_STAGE(bufoff, gbase, voff) do { _Pragma("unroll") for (int _i = 0; _i < 2; ++_i) \
;         __builtin_amdgcn_global_load_lds((const unsigned*)((const char*)(gbase) + (voff)[_i]), (LAS unsigned*)(lds + (bufoff) + ldsw + _i * 8192), 16, 0, 0); } while (0)
; #define PG8_LDA(dst, b, h) do { _Pragma("unroll") for (int m = 0; m < 4; ++m) _Pragma("unroll") for (int k = 0; k < 2; ++k) dst[m][k] = *(const LAS bf16x8*)(lds + PG8_SA(b, h) + aoff + m * 2048 + k * 1024); } while (0)
; #define PG8_MMA(ai, bj, At, Bt) do { __builtin_amdgcn_s_setprio(1); _Pragma("unroll") for (int m = 0; m < 4; ++m) _Pragma("unroll") for (int n = 0; n < 2; ++n) _Pragma("unroll") for (int k = 0; k < 2; ++k) \
;         acc[ai][bj][m][n] = __builtin_amdgcn_mfma_f32_16x16x32_bf16(Bt[n][k], At[m][k], acc[ai][bj][m][n], 0, 0, 0); __builtin_amdgcn_s_setprio(0); } while (0)
; #define PG8_WAIT_V(n) asm volatile("s_waitcnt vmcnt(" #n ")" ::: "memory")
; #define PG8_WAIT_L(n) asm volatile("s_waitcnt lgkmcnt(" #n ")" ::: "memory")
; #define PG8_BAR __builtin_amdgcn_s_barrier()
; #define PG8_SCHED __builtin_amdgcn_sched_barrier(0)
; template <class Epi, class Sched>
; __device__ __forceinline__ void gemm_phase(LAS unsigned char* lds, const int K, const Sched& S, const Epi& E) {
;     ...
;             PG8_LDA(At, 1, 1); PG8_STAGE(PG8_SB(1, 0), b3, voffB); PG8_STAGE(PG8_SB(1, 1), b3 + hstep, voffB); PG8_STAGE(PG8_SA(1, 0), a3, voffA);
;             PG8_WAIT_V(8); PG8_WAIT_L(0); PG8_BAR; PG8_MMA(1, 0, At, B0); PG8_MMA(1, 1, At, B1); PG8_BAR; PG8_SCHED;
;         }
;         if (wr == 0) PG8_BAR;
	s_setprio 0
	s_add_i32 s14, s16, s1
	v_lshl_add_u64 v[180:181], v[180:181], 0, s[36:37]
	s_mov_b32 m0, s14
	ds_read_b128 v[200:203], v151 offset:49152
	ds_read_b128 v[204:207], v151 offset:50176
	ds_read_b128 v[208:211], v151 offset:51200
	ds_read_b128 v[212:215], v151 offset:52224
	ds_read_b128 v[216:219], v151 offset:53248
	ds_read_b128 v[220:223], v151 offset:54272
	ds_read_b128 v[224:227], v151 offset:55296
	ds_read_b128 v[228:231], v151 offset:56320
	global_load_lds_dwordx4 v[180:181], off
	s_add_i32 m0, s14, 0x2000
	s_add_u32 s14, s38, 0x100080
	v_lshl_add_u64 v[180:181], v[182:183], 0, s[36:37]
	s_addc_u32 s15, s39, 0
	s_add_i32 s16, s17, s1
	global_load_lds_dwordx4 v[180:181], off
	v_lshl_add_u64 v[180:181], s[14:15], 0, v[128:129]
	s_mov_b32 m0, s16
	s_nop 0
	global_load_lds_dwordx4 v[180:181], off
	v_lshl_add_u64 v[180:181], s[14:15], 0, v[138:139]
	s_add_i32 m0, s16, 0x2000
	s_nop 0
	global_load_lds_dwordx4 v[180:181], off
	v_lshl_add_u64 v[180:181], v[232:233], 0, s[36:37]
	s_mov_b32 m0, s11
	s_nop 0
	global_load_lds_dwordx4 v[180:181], off
	v_lshl_add_u64 v[180:181], v[234:235], 0, s[36:37]
	s_mov_b32 m0, s12
	s_nop 0
	global_load_lds_dwordx4 v[180:181], off
	s_waitcnt vmcnt(8)
	s_waitcnt lgkmcnt(0)
	s_setprio 1
	s_barrier
	v_mfma_f32_16x16x32_bf16 v[60:63], v[152:155], v[200:203], v[60:63]
	v_mfma_f32_16x16x32_bf16 v[56:59], v[160:163], v[200:203], v[56:59]
	v_mfma_f32_16x16x32_bf16 v[44:47], v[152:155], v[208:211], v[44:47]
	v_mfma_f32_16x16x32_bf16 v[40:43], v[160:163], v[208:211], v[40:43]
	v_mfma_f32_16x16x32_bf16 v[28:31], v[152:155], v[216:219], v[28:31]
	v_mfma_f32_16x16x32_bf16 v[24:27], v[160:163], v[216:219], v[24:27]
	v_mfma_f32_16x16x32_bf16 v[12:15], v[152:155], v[224:227], v[12:15]
	v_mfma_f32_16x16x32_bf16 v[8:11], v[160:163], v[224:227], v[8:11]
	v_mfma_f32_16x16x32_bf16 v[60:63], v[156:159], v[204:207], v[60:63]
	v_mfma_f32_16x16x32_bf16 v[56:59], v[164:167], v[204:207], v[56:59]
	v_mfma_f32_16x16x32_bf16 v[44:47], v[156:159], v[212:215], v[44:47]
	v_mfma_f32_16x16x32_bf16 v[40:43], v[164:167], v[212:215], v[40:43]
	v_mfma_f32_16x16x32_bf16 v[28:31], v[156:159], v[220:223], v[28:31]
	v_mfma_f32_16x16x32_bf16 v[24:27], v[164:167], v[220:223], v[24:27]
	v_mfma_f32_16x16x32_bf16 v[12:15], v[156:159], v[228:231], v[12:15]
	v_mfma_f32_16x16x32_bf16 v[8:11], v[164:167], v[228:231], v[8:11]
	s_setprio 0
	s_setprio 1
	v_mfma_f32_16x16x32_bf16 v[52:55], v[184:187], v[200:203], v[52:55]
	v_mfma_f32_16x16x32_bf16 v[48:51], v[192:195], v[200:203], v[48:51]
	v_mfma_f32_16x16x32_bf16 v[36:39], v[184:187], v[208:211], v[36:39]
	v_mfma_f32_16x16x32_bf16 v[32:35], v[192:195], v[208:211], v[32:35]
	v_mfma_f32_16x16x32_bf16 v[20:23], v[184:187], v[216:219], v[20:23]
	v_mfma_f32_16x16x32_bf16 v[16:19], v[192:195], v[216:219], v[16:19]
	v_mfma_f32_16x16x32_bf16 v[4:7], v[184:187], v[224:227], v[4:7]
	v_mfma_f32_16x16x32_bf16 v[0:3], v[192:195], v[224:227], v[0:3]
	v_mfma_f32_16x16x32_bf16 v[52:55], v[188:191], v[204:207], v[52:55]
	v_mfma_f32_16x16x32_bf16 v[48:51], v[196:199], v[204:207], v[48:51]
	v_mfma_f32_16x16x32_bf16 v[36:39], v[188:191], v[212:215], v[36:39]
	v_mfma_f32_16x16x32_bf16 v[32:35], v[196:199], v[212:215], v[32:35]
	v_mfma_f32_16x16x32_bf16 v[20:23], v[188:191], v[220:223], v[20:23]
	v_mfma_f32_16x16x32_bf16 v[16:19], v[196:199], v[220:223], v[16:19]
	v_mfma_f32_16x16x32_bf16 v[4:7], v[188:191], v[228:231], v[4:7]
	v_mfma_f32_16x16x32_bf16 v[0:3], v[196:199], v[228:231], v[0:3]
	s_barrier
	s_setprio 0
	s_add_i32 s13, s13, 2
	s_add_u32 s8, s8, 0x100
	s_addc_u32 s9, s9, 0
	s_cmp_gt_u32 s13, 61
	s_cbranch_scc0 .LBB0_511
	s_cmpk_lt_u32 s0, 0x100
	s_cbranch_scc0 .LBB0_514
	s_barrier

; #define PG8_STAGE(bufoff, gbase, voff) do { _Pragma("unroll") for (int _i = 0; _i < 2; ++_i) \
;         __builtin_amdgcn_global_load_lds((const unsigned*)((const char*)(gbase) + (voff)[_i]), (LAS unsigned*)(lds + (bufoff) + ldsw + _i * 8192), 16, 0, 0); } while (0)
; #define PG8_LDA(dst, b, h) do { _Pragma("unroll") for (int m = 0; m < 4; ++m) _Pragma("unroll") for (int k = 0; k < 2; ++k) dst[m][k] = *(const LAS bf16x8*)(lds + PG8_SA(b, h) + aoff + m * 2048 + k * 1024); } while (0)
; #define PG8_LDB(dst, b, h) do { _Pragma("unroll") for (int n = 0; n < 2; ++n) _Pragma("unroll") for (int k = 0; k < 2; ++k) dst[n][k] = *(const LAS bf16x8*)(lds + PG8_SB(b, h) + boff + n * 2048 + k * 1024); } while (0)
; #define PG8_MMA(ai, bj, At, Bt) do { __builtin_amdgcn_s_setprio(1); _Pragma("unroll") for (int m = 0; m < 4; ++m) _Pragma("unroll") for (int n = 0; n < 2; ++n) _Pragma("unroll") for (int k = 0; k < 2; ++k) \
;         acc[ai][bj][m][n] = __builtin_amdgcn_mfma_f32_16x16x32_bf16(Bt[n][k], At[m][k], acc[ai][bj][m][n], 0, 0, 0); __builtin_amdgcn_s_setprio(0); } while (0)
; #define PG8_WAIT_V(n) asm volatile("s_waitcnt vmcnt(" #n ")" ::: "memory")
; #define PG8_WAIT_L(n) asm volatile("s_waitcnt lgkmcnt(" #n ")" ::: "memory")
; #define PG8_BAR __builtin_amdgcn_s_barrier()
; #define PG8_SCHED __builtin_amdgcn_sched_barrier(0)
; template <class Epi, class Sched>
; __device__ __forceinline__ void gemm_phase(LAS unsigned char* lds, const int K, const Sched& S, const Epi& E) {
;     ...
;             const bool last = (t == nt - 2);
;             const char* a1 = cA + (size_t)(t + 1) * kstep;
;             const char* a2 = last ? nA : cA + (size_t)(t + 2) * kstep; const char* b2 = last ? nB : cB + (size_t)(t + 2) * kstep;
;             const char* a3 = a2 + kstep; const char* b3 = b2 + kstep;
;             PG8_LDB(B0, 0, 0); PG8_LDB(B1, 0, 1); PG8_SCHED; PG8_LDA(At, 0, 0); PG8_STAGE(PG8_SA(1, 1), a1 + hstep, voffA);
;             PG8_WAIT_V(8); PG8_WAIT_L(0); PG8_BAR; PG8_MMA(0, 0, At, B0); PG8_MMA(0, 1, At, B1); PG8_BAR; PG8_SCHED;
;             PG8_LDA(At, 0, 1); PG8_STAGE(PG8_SB(0, 0), b2, voffB); PG8_STAGE(PG8_SB(0, 1), b2 + hstep, voffB); PG8_STAGE(PG8_SA(0, 0), a2, voffA);
.LBB0_533:
	s_add_u32 s14, s50, s11
	s_addc_u32 s15, s51, 0
	s_add_u32 s16, s14, 0x100
	s_addc_u32 s17, s15, 0
	s_and_b64 s[12:13], s[54:55], exec
	s_cselect_b32 s59, s45, s17
	s_cselect_b32 s58, s44, s16
	s_add_u32 s11, s8, s11
	s_addc_u32 s12, s9, 0
	s_add_u32 s11, s11, 0x100
	s_addc_u32 s16, s12, 0
	s_add_i32 s21, 0, 0x10000
	s_and_b64 s[12:13], s[54:55], exec
	s_cselect_b32 s61, s47, s16
	s_cselect_b32 s60, s46, s11
	s_add_i32 s25, 0, 0x14000
	s_add_u32 s64, s14, 0x10080
	s_addc_u32 s65, s15, 0
	s_add_i32 s19, s21, s3
	s_add_i32 m0, s26, 0xc000
	s_add_i32 s28, s26, 0xe000
	s_add_i32 s15, s19, 0x2000
	v_add_u32_e32 v146, s21, v148
	s_add_u32 s62, s60, 0x10000
	ds_read_b128 v[152:155], v146
	ds_read_b128 v[156:159], v146 offset:1024
	ds_read_b128 v[160:163], v146 offset:2048
	ds_read_b128 v[164:167], v146 offset:3072
	v_add_u32_e32 v146, s25, v148
	s_addc_u32 s63, s61, 0
	s_add_i32 s17, s25, s3
	ds_read_b128 v[184:187], v146
	ds_read_b128 v[188:191], v146 offset:1024
	ds_read_b128 v[192:195], v146 offset:2048
	ds_read_b128 v[196:199], v146 offset:3072
	s_add_i32 s16, s17, 0x2000
	s_add_i32 s14, 0, 0x18000
	s_add_i32 s13, 0, 0x1c000
	s_add_u32 s56, s58, 0x10000
	s_addc_u32 s57, s59, 0
	s_add_i32 s12, s14, s3
	s_add_i32 s11, s12, 0x2000
	s_add_u32 s54, s60, 0x10080
	s_addc_u32 s55, s61, 0
	s_add_i32 s25, s13, s3
	s_add_i32 s21, s25, 0x2000
	v_lshl_add_u64 v[146:147], s[64:65], 0, v[144:145]
	ds_read_b128 v[200:203], v150
	ds_read_b128 v[204:207], v150 offset:1024
	ds_read_b128 v[208:211], v150 offset:2048
	ds_read_b128 v[212:215], v150 offset:3072
	ds_read_b128 v[216:219], v150 offset:4096
	ds_read_b128 v[220:223], v150 offset:5120
	ds_read_b128 v[224:227], v150 offset:6144
	ds_read_b128 v[228:231], v150 offset:7168
	global_load_lds_dwordx4 v[146:147], off
	v_lshl_add_u64 v[146:147], s[64:65], 0, v[140:141]
	s_mov_b32 m0, s28
	s_nop 0
	global_load_lds_dwordx4 v[146:147], off
	s_waitcnt vmcnt(8)
	s_waitcnt lgkmcnt(0)
	s_setprio 1
	s_barrier
	v_mfma_f32_16x16x32_bf16 v[124:127], v[152:155], v[200:203], v[124:127]
	v_mfma_f32_16x16x32_bf16 v[120:123], v[160:163], v[200:203], v[120:123]
	v_mfma_f32_16x16x32_bf16 v[112:115], v[152:155], v[208:211], v[112:115]
	v_mfma_f32_16x16x32_bf16 v[104:107], v[160:163], v[208:211], v[104:107]
	v_mfma_f32_16x16x32_bf16 v[96:99], v[152:155], v[216:219], v[96:99]
	v_mfma_f32_16x16x32_bf16 v[88:91], v[160:163], v[216:219], v[88:91]
	v_mfma_f32_16x16x32_bf16 v[80:83], v[152:155], v[224:227], v[80:83]
	v_mfma_f32_16x16x32_bf16 v[72:75], v[160:163], v[224:227], v[72:75]
	v_mfma_f32_16x16x32_bf16 v[124:127], v[156:159], v[204:207], v[124:127]
	v_mfma_f32_16x16x32_bf16 v[120:123], v[164:167], v[204:207], v[120:123]
	v_mfma_f32_16x16x32_bf16 v[112:115], v[156:159], v[212:215], v[112:115]
	v_mfma_f32_16x16x32_bf16 v[104:107], v[164:167], v[212:215], v[104:107]
	v_mfma_f32_16x16x32_bf16 v[96:99], v[156:159], v[220:223], v[96:99]
	v_mfma_f32_16x16x32_bf16 v[88:91], v[164:167], v[220:223], v[88:91]
	v_mfma_f32_16x16x32_bf16 v[80:83], v[156:159], v[228:231], v[80:83]
	v_mfma_f32_16x16x32_bf16 v[72:75], v[164:167], v[228:231], v[72:75]
	s_setprio 0
	s_setprio 1
	v_mfma_f32_16x16x32_bf16 v[116:119], v[184:187], v[200:203], v[116:119]
	v_mfma_f32_16x16x32_bf16 v[108:111], v[192:195], v[200:203], v[108:111]
	v_mfma_f32_16x16x32_bf16 v[100:103], v[184:187], v[208:211], v[100:103]
	v_mfma_f32_16x16x32_bf16 v[92:95], v[192:195], v[208:211], v[92:95]
	v_mfma_f32_16x16x32_bf16 v[84:87], v[184:187], v[216:219], v[84:87]
	v_mfma_f32_16x16x32_bf16 v[76:79], v[192:195], v[216:219], v[76:79]
	v_mfma_f32_16x16x32_bf16 v[68:71], v[184:187], v[224:227], v[68:71]
	v_mfma_f32_16x16x32_bf16 v[64:67], v[192:195], v[224:227], v[64:67]
	v_mfma_f32_16x16x32_bf16 v[116:119], v[188:191], v[204:207], v[116:119]
	v_mfma_f32_16x16x32_bf16 v[108:111], v[196:199], v[204:207], v[108:111]
	v_mfma_f32_16x16x32_bf16 v[100:103], v[188:191], v[212:215], v[100:103]
	v_mfma_f32_16x16x32_bf16 v[92:95], v[196:199], v[212:215], v[92:95]
	v_mfma_f32_16x16x32_bf16 v[84:87], v[188:191], v[220:223], v[84:87]
	v_mfma_f32_16x16x32_bf16 v[76:79], v[196:199], v[220:223], v[76:79]
	v_mfma_f32_16x16x32_bf16 v[68:71], v[188:191], v[228:231], v[68:71]
	v_mfma_f32_16x16x32_bf16 v[64:67], v[196:199], v[228:231], v[64:67]
	s_barrier
	s_setprio 0
	s_mov_b32 m0, s19
	v_lshl_add_u64 v[146:147], s[60:61], 0, v[142:143]
	ds_read_b128 v[200:203], v150 offset:16384
	ds_read_b128 v[204:207], v150 offset:17408
	ds_read_b128 v[208:211], v150 offset:18432
	ds_read_b128 v[212:215], v150 offset:19456
	ds_read_b128 v[216:219], v150 offset:20480
	ds_read_b128 v[220:223], v150 offset:21504
	ds_read_b128 v[224:227], v150 offset:22528
	ds_read_b128 v[228:231], v150 offset:23552
	global_load_lds_dwordx4 v[146:147], off
	v_lshl_add_u64 v[180:181], s[60:61], 0, v[138:139]
	s_mov_b32 m0, s15
	v_lshl_add_u64 v[182:183], s[62:63], 0, v[142:143]
	global_load_lds_dwordx4 v[180:181], off
	s_mov_b32 m0, s17
	v_lshl_add_u64 v[232:233], s[58:59], 0, v[140:141]
	global_load_lds_dwordx4 v[182:183], off
	v_lshl_add_u64 v[182:183], s[62:63], 0, v[138:139]
	s_mov_b32 m0, s16
	s_nop 0
	global_load_lds_dwordx4 v[182:183], off
	v_lshl_add_u64 v[182:183], s[58:59], 0, v[144:145]
	s_mov_b32 m0, s26
	s_nop 0
	global_load_lds_dwordx4 v[182:183], off
	s_mov_b32 m0, s27
	s_nop 0
	global_load_lds_dwordx4 v[232:233], off
	s_waitcnt vmcnt(8)
	s_waitcnt lgkmcnt(0)
	s_setprio 1
	s_barrier
; #define PG8_STAGE(bufoff, gbase, voff) do { _Pragma("unroll") for (int _i = 0; _i < 2; ++_i) \
;         __builtin_amdgcn_global_load_lds((const unsigned*)((const char*)(gbase) + (voff)[_i]), (LAS unsigned*)(lds + (bufoff) + ldsw + _i * 8192), 16, 0, 0); } while (0)
; #define PG8_LDA(dst, b, h) do { _Pragma("unroll") for (int m = 0; m < 4; ++m) _Pragma("unroll") for (int k = 0; k < 2; ++k) dst[m][k] = *(const LAS bf16x8*)(lds + PG8_SA(b, h) + aoff + m * 2048 + k * 1024); } while (0)
; #define PG8_LDB(dst, b, h) do { _Pragma("unroll") for (int n = 0; n < 2; ++n) _Pragma("unroll") for (int k = 0; k < 2; ++k) dst[n][k] = *(const LAS bf16x8*)(lds + PG8_SB(b, h) + boff + n * 2048 + k * 1024); } while (0)
; #define PG8_MMA(ai, bj, At, Bt) do { __builtin_amdgcn_s_setprio(1); _Pragma("unroll") for (int m = 0; m < 4; ++m) _Pragma("unroll") for (int n = 0; n < 2; ++n) _Pragma("unroll") for (int k = 0; k < 2; ++k) \
;         acc[ai][bj][m][n] = __builtin_amdgcn_mfma_f32_16x16x32_bf16(Bt[n][k], At[m][k], acc[ai][bj][m][n], 0, 0, 0); __builtin_amdgcn_s_setprio(0); } while (0)
; #define PG8_WAIT_V(n) asm volatile("s_waitcnt vmcnt(" #n ")" ::: "memory")
; #define PG8_WAIT_L(n) asm volatile("s_waitcnt lgkmcnt(" #n ")" ::: "memory")
; #define PG8_BAR __builtin_amdgcn_s_barrier()
; #define PG8_SCHED __builtin_amdgcn_sched_barrier(0)
; template <class Epi, class Sched>
; __device__ __forceinline__ void gemm_phase(LAS unsigned char* lds, const int K, const Sched& S, const Epi& E) {
;     ...
;             PG8_WAIT_V(8); PG8_WAIT_L(0); PG8_BAR; PG8_MMA(1, 0, At, B0); PG8_MMA(1, 1, At, B1); PG8_BAR; PG8_SCHED;
;             PG8_LDB(B0, 1, 0); PG8_LDB(B1, 1, 1); PG8_SCHED; PG8_LDA(At, 1, 0); PG8_STAGE(PG8_SA(0, 1), a2 + hstep, voffA);
;             PG8_WAIT_V(8); PG8_WAIT_L(0); PG8_BAR; PG8_MMA(0, 0, At, B0); PG8_MMA(0, 1, At, B1); PG8_BAR; PG8_SCHED;
	v_mfma_f32_16x16x32_bf16 v[60:63], v[152:155], v[200:203], v[60:63]
	v_mfma_f32_16x16x32_bf16 v[56:59], v[160:163], v[200:203], v[56:59]
	v_mfma_f32_16x16x32_bf16 v[48:51], v[152:155], v[208:211], v[48:51]
	v_mfma_f32_16x16x32_bf16 v[40:43], v[160:163], v[208:211], v[40:43]
	v_mfma_f32_16x16x32_bf16 v[32:35], v[152:155], v[216:219], v[32:35]
	v_mfma_f32_16x16x32_bf16 v[24:27], v[160:163], v[216:219], v[24:27]
	v_mfma_f32_16x16x32_bf16 v[16:19], v[152:155], v[224:227], v[16:19]
	v_mfma_f32_16x16x32_bf16 v[8:11], v[160:163], v[224:227], v[8:11]
	v_mfma_f32_16x16x32_bf16 v[60:63], v[156:159], v[204:207], v[60:63]
	v_mfma_f32_16x16x32_bf16 v[56:59], v[164:167], v[204:207], v[56:59]
	v_mfma_f32_16x16x32_bf16 v[48:51], v[156:159], v[212:215], v[48:51]
	v_mfma_f32_16x16x32_bf16 v[40:43], v[164:167], v[212:215], v[40:43]
	v_mfma_f32_16x16x32_bf16 v[32:35], v[156:159], v[220:223], v[32:35]
	v_mfma_f32_16x16x32_bf16 v[24:27], v[164:167], v[220:223], v[24:27]
	v_mfma_f32_16x16x32_bf16 v[16:19], v[156:159], v[228:231], v[16:19]
	v_mfma_f32_16x16x32_bf16 v[8:11], v[164:167], v[228:231], v[8:11]
	s_setprio 0
	s_setprio 1
	v_mfma_f32_16x16x32_bf16 v[52:55], v[184:187], v[200:203], v[52:55]
	v_mfma_f32_16x16x32_bf16 v[44:47], v[192:195], v[200:203], v[44:47]
	v_mfma_f32_16x16x32_bf16 v[36:39], v[184:187], v[208:211], v[36:39]
	v_mfma_f32_16x16x32_bf16 v[28:31], v[192:195], v[208:211], v[28:31]
	v_mfma_f32_16x16x32_bf16 v[20:23], v[184:187], v[216:219], v[20:23]
	v_mfma_f32_16x16x32_bf16 v[12:15], v[192:195], v[216:219], v[12:15]
	v_mfma_f32_16x16x32_bf16 v[4:7], v[184:187], v[224:227], v[4:7]
	v_mfma_f32_16x16x32_bf16 v[0:3], v[192:195], v[224:227], v[0:3]
	v_mfma_f32_16x16x32_bf16 v[52:55], v[188:191], v[204:207], v[52:55]
	v_mfma_f32_16x16x32_bf16 v[44:47], v[196:199], v[204:207], v[44:47]
	v_mfma_f32_16x16x32_bf16 v[36:39], v[188:191], v[212:215], v[36:39]
	v_mfma_f32_16x16x32_bf16 v[28:31], v[196:199], v[212:215], v[28:31]
	v_mfma_f32_16x16x32_bf16 v[20:23], v[188:191], v[220:223], v[20:23]
	v_mfma_f32_16x16x32_bf16 v[12:15], v[196:199], v[220:223], v[12:15]
	v_mfma_f32_16x16x32_bf16 v[4:7], v[188:191], v[228:231], v[4:7]
	v_mfma_f32_16x16x32_bf16 v[0:3], v[196:199], v[228:231], v[0:3]
	s_barrier
	s_setprio 0
	v_add_u32_e32 v151, s14, v148
	ds_read_b128 v[152:155], v151
	ds_read_b128 v[156:159], v151 offset:1024
	ds_read_b128 v[160:163], v151 offset:2048
	ds_read_b128 v[164:167], v151 offset:3072
	v_add_u32_e32 v151, s13, v148
	ds_read_b128 v[184:187], v151
	ds_read_b128 v[188:191], v151 offset:1024
	ds_read_b128 v[192:195], v151 offset:2048
	ds_read_b128 v[196:199], v151 offset:3072
	s_mov_b32 m0, s66
	v_lshl_add_u64 v[234:235], s[56:57], 0, v[144:145]
	ds_read_b128 v[200:203], v150 offset:32768
	ds_read_b128 v[204:207], v150 offset:33792
	ds_read_b128 v[208:211], v150 offset:34816
	ds_read_b128 v[212:215], v150 offset:35840
	ds_read_b128 v[216:219], v150 offset:36864
	ds_read_b128 v[220:223], v150 offset:37888
	ds_read_b128 v[224:227], v150 offset:38912
	ds_read_b128 v[228:231], v150 offset:39936
	global_load_lds_dwordx4 v[234:235], off
	v_lshl_add_u64 v[234:235], s[56:57], 0, v[140:141]
	s_mov_b32 m0, s67
	s_nop 0
	global_load_lds_dwordx4 v[234:235], off
	s_waitcnt vmcnt(8)
	s_waitcnt lgkmcnt(0)
	s_setprio 1
	s_barrier
	v_mfma_f32_16x16x32_bf16 v[124:127], v[152:155], v[200:203], v[124:127]
	v_mfma_f32_16x16x32_bf16 v[120:123], v[160:163], v[200:203], v[120:123]
	v_mfma_f32_16x16x32_bf16 v[112:115], v[152:155], v[208:211], v[112:115]
	v_mfma_f32_16x16x32_bf16 v[104:107], v[160:163], v[208:211], v[104:107]
	v_mfma_f32_16x16x32_bf16 v[96:99], v[152:155], v[216:219], v[96:99]
	v_mfma_f32_16x16x32_bf16 v[88:91], v[160:163], v[216:219], v[88:91]
	v_mfma_f32_16x16x32_bf16 v[80:83], v[152:155], v[224:227], v[80:83]
	v_mfma_f32_16x16x32_bf16 v[72:75], v[160:163], v[224:227], v[72:75]
	v_mfma_f32_16x16x32_bf16 v[124:127], v[156:159], v[204:207], v[124:127]
	v_mfma_f32_16x16x32_bf16 v[120:123], v[164:167], v[204:207], v[120:123]
	v_mfma_f32_16x16x32_bf16 v[112:115], v[156:159], v[212:215], v[112:115]
	v_mfma_f32_16x16x32_bf16 v[104:107], v[164:167], v[212:215], v[104:107]
	v_mfma_f32_16x16x32_bf16 v[96:99], v[156:159], v[220:223], v[96:99]
	v_mfma_f32_16x16x32_bf16 v[88:91], v[164:167], v[220:223], v[88:91]
	v_mfma_f32_16x16x32_bf16 v[80:83], v[156:159], v[228:231], v[80:83]
	v_mfma_f32_16x16x32_bf16 v[72:75], v[164:167], v[228:231], v[72:75]
	s_setprio 0
	s_setprio 1
	v_mfma_f32_16x16x32_bf16 v[116:119], v[184:187], v[200:203], v[116:119]
	v_mfma_f32_16x16x32_bf16 v[108:111], v[192:195], v[200:203], v[108:111]
	v_mfma_f32_16x16x32_bf16 v[100:103], v[184:187], v[208:211], v[100:103]
	v_mfma_f32_16x16x32_bf16 v[92:95], v[192:195], v[208:211], v[92:95]
	v_mfma_f32_16x16x32_bf16 v[84:87], v[184:187], v[216:219], v[84:87]
	v_mfma_f32_16x16x32_bf16 v[76:79], v[192:195], v[216:219], v[76:79]
	v_mfma_f32_16x16x32_bf16 v[68:71], v[184:187], v[224:227], v[68:71]
	v_mfma_f32_16x16x32_bf16 v[64:67], v[192:195], v[224:227], v[64:67]
	v_mfma_f32_16x16x32_bf16 v[116:119], v[188:191], v[204:207], v[116:119]
	v_mfma_f32_16x16x32_bf16 v[108:111], v[196:199], v[204:207], v[108:111]
	v_mfma_f32_16x16x32_bf16 v[100:103], v[188:191], v[212:215], v[100:103]
	v_mfma_f32_16x16x32_bf16 v[92:95], v[196:199], v[212:215], v[92:95]
	v_mfma_f32_16x16x32_bf16 v[84:87], v[188:191], v[220:223], v[84:87]
	v_mfma_f32_16x16x32_bf16 v[76:79], v[196:199], v[220:223], v[76:79]
	v_mfma_f32_16x16x32_bf16 v[68:71], v[188:191], v[228:231], v[68:71]
	v_mfma_f32_16x16x32_bf16 v[64:67], v[196:199], v[228:231], v[64:67]
	s_barrier
; #define PG8_STAGE(bufoff, gbase, voff) do { _Pragma("unroll") for (int _i = 0; _i < 2; ++_i) \
;         __builtin_amdgcn_global_load_lds((const unsigned*)((const char*)(gbase) + (voff)[_i]), (LAS unsigned*)(lds + (bufoff) + ldsw + _i * 8192), 16, 0, 0); } while (0)
; #define PG8_LDA(dst, b, h) do { _Pragma("unroll") for (int m = 0; m < 4; ++m) _Pragma("unroll") for (int k = 0; k < 2; ++k) dst[m][k] = *(const LAS bf16x8*)(lds + PG8_SA(b, h) + aoff + m * 2048 + k * 1024); } while (0)
; #define PG8_MMA(ai, bj, At, Bt) do { __builtin_amdgcn_s_setprio(1); _Pragma("unroll") for (int m = 0; m < 4; ++m) _Pragma("unroll") for (int n = 0; n < 2; ++n) _Pragma("unroll") for (int k = 0; k < 2; ++k) \
;         acc[ai][bj][m][n] = __builtin_amdgcn_mfma_f32_16x16x32_bf16(Bt[n][k], At[m][k], acc[ai][bj][m][n], 0, 0, 0); __builtin_amdgcn_s_setprio(0); } while (0)
; #define PG8_WAIT_V(n) asm volatile("s_waitcnt vmcnt(" #n ")" ::: "memory")
; #define PG8_WAIT_L(n) asm volatile("s_waitcnt lgkmcnt(" #n ")" ::: "memory")
; #define PG8_BAR __builtin_amdgcn_s_barrier()
; #define PG8_SCHED __builtin_amdgcn_sched_barrier(0)
; template <class Epi, class Sched>
; __device__ __forceinline__ void gemm_phase(LAS unsigned char* lds, const int K, const Sched& S, const Epi& E) {
;     ...
;             PG8_LDA(At, 1, 1); PG8_STAGE(PG8_SB(1, 0), b3, voffB); PG8_STAGE(PG8_SB(1, 1), b3 + hstep, voffB); PG8_STAGE(PG8_SA(1, 0), a3, voffA);
;             PG8_WAIT_V(8); PG8_WAIT_L(0); PG8_BAR; PG8_MMA(1, 0, At, B0); PG8_MMA(1, 1, At, B1); PG8_BAR; PG8_SCHED;
;         }
;         if (wr == 0) PG8_BAR;
	s_setprio 0
	s_mov_b32 m0, s12
	v_lshl_add_u64 v[146:147], v[146:147], 0, s[36:37]
	ds_read_b128 v[200:203], v150 offset:49152
	ds_read_b128 v[204:207], v150 offset:50176
	ds_read_b128 v[208:211], v150 offset:51200
	ds_read_b128 v[212:215], v150 offset:52224
	ds_read_b128 v[216:219], v150 offset:53248
	ds_read_b128 v[220:223], v150 offset:54272
	ds_read_b128 v[224:227], v150 offset:55296
	ds_read_b128 v[228:231], v150 offset:56320
	global_load_lds_dwordx4 v[146:147], off
	v_lshl_add_u64 v[146:147], v[180:181], 0, s[36:37]
	s_mov_b32 m0, s11
	s_nop 0
	global_load_lds_dwordx4 v[146:147], off
	v_lshl_add_u64 v[146:147], s[54:55], 0, v[142:143]
	s_mov_b32 m0, s25
	s_nop 0
	global_load_lds_dwordx4 v[146:147], off
	v_lshl_add_u64 v[146:147], s[54:55], 0, v[138:139]
	s_mov_b32 m0, s21
	s_nop 0
	global_load_lds_dwordx4 v[146:147], off
	v_lshl_add_u64 v[146:147], v[182:183], 0, s[36:37]
	s_mov_b32 m0, s0
	s_nop 0
	global_load_lds_dwordx4 v[146:147], off
	v_lshl_add_u64 v[146:147], v[232:233], 0, s[36:37]
	s_mov_b32 m0, s1
	s_nop 0
	global_load_lds_dwordx4 v[146:147], off
	s_waitcnt vmcnt(8)
	s_waitcnt lgkmcnt(0)
	s_setprio 1
	s_barrier
	v_mfma_f32_16x16x32_bf16 v[60:63], v[152:155], v[200:203], v[60:63]
	v_mfma_f32_16x16x32_bf16 v[56:59], v[160:163], v[200:203], v[56:59]
	v_mfma_f32_16x16x32_bf16 v[48:51], v[152:155], v[208:211], v[48:51]
	v_mfma_f32_16x16x32_bf16 v[40:43], v[160:163], v[208:211], v[40:43]
	v_mfma_f32_16x16x32_bf16 v[32:35], v[152:155], v[216:219], v[32:35]
	v_mfma_f32_16x16x32_bf16 v[24:27], v[160:163], v[216:219], v[24:27]
	v_mfma_f32_16x16x32_bf16 v[16:19], v[152:155], v[224:227], v[16:19]
	v_mfma_f32_16x16x32_bf16 v[8:11], v[160:163], v[224:227], v[8:11]
	v_mfma_f32_16x16x32_bf16 v[60:63], v[156:159], v[204:207], v[60:63]
	v_mfma_f32_16x16x32_bf16 v[56:59], v[164:167], v[204:207], v[56:59]
	v_mfma_f32_16x16x32_bf16 v[48:51], v[156:159], v[212:215], v[48:51]
	v_mfma_f32_16x16x32_bf16 v[40:43], v[164:167], v[212:215], v[40:43]
	v_mfma_f32_16x16x32_bf16 v[32:35], v[156:159], v[220:223], v[32:35]
	v_mfma_f32_16x16x32_bf16 v[24:27], v[164:167], v[220:223], v[24:27]
	v_mfma_f32_16x16x32_bf16 v[16:19], v[156:159], v[228:231], v[16:19]
	v_mfma_f32_16x16x32_bf16 v[8:11], v[164:167], v[228:231], v[8:11]
	s_setprio 0
	s_setprio 1
	v_mfma_f32_16x16x32_bf16 v[52:55], v[184:187], v[200:203], v[52:55]
	v_mfma_f32_16x16x32_bf16 v[44:47], v[192:195], v[200:203], v[44:47]
	v_mfma_f32_16x16x32_bf16 v[36:39], v[184:187], v[208:211], v[36:39]
	v_mfma_f32_16x16x32_bf16 v[28:31], v[192:195], v[208:211], v[28:31]
	v_mfma_f32_16x16x32_bf16 v[20:23], v[184:187], v[216:219], v[20:23]
	v_mfma_f32_16x16x32_bf16 v[12:15], v[192:195], v[216:219], v[12:15]
	v_mfma_f32_16x16x32_bf16 v[4:7], v[184:187], v[224:227], v[4:7]
	v_mfma_f32_16x16x32_bf16 v[0:3], v[192:195], v[224:227], v[0:3]
	v_mfma_f32_16x16x32_bf16 v[52:55], v[188:191], v[204:207], v[52:55]
	v_mfma_f32_16x16x32_bf16 v[44:47], v[196:199], v[204:207], v[44:47]
	v_mfma_f32_16x16x32_bf16 v[36:39], v[188:191], v[212:215], v[36:39]
	v_mfma_f32_16x16x32_bf16 v[28:31], v[196:199], v[212:215], v[28:31]
	v_mfma_f32_16x16x32_bf16 v[20:23], v[188:191], v[220:223], v[20:23]
	v_mfma_f32_16x16x32_bf16 v[12:15], v[196:199], v[220:223], v[12:15]
	v_mfma_f32_16x16x32_bf16 v[4:7], v[188:191], v[228:231], v[4:7]
	v_mfma_f32_16x16x32_bf16 v[0:3], v[196:199], v[228:231], v[0:3]
	s_barrier
	s_setprio 0
	s_movk_i32 s11, 0x100
	s_andn2_b64 vcc, exec, s[52:53]
	s_mov_b64 s[54:55], -1
	s_mov_b64 s[52:53], 0
	s_cbranch_vccz .LBB0_533
	s_and_b64 vcc, exec, s[40:41]
	s_cbranch_vccz .LBB0_536
	s_barrier

; #define PG8_STAGE(bufoff, gbase, voff) do { _Pragma("unroll") for (int _i = 0; _i < 2; ++_i) \
;         __builtin_amdgcn_global_load_lds((const unsigned*)((const char*)(gbase) + (voff)[_i]), (LAS unsigned*)(lds + (bufoff) + ldsw + _i * 8192), 16, 0, 0); } while (0)
; #define PG8_LDA(dst, b, h) do { _Pragma("unroll") for (int m = 0; m < 4; ++m) _Pragma("unroll") for (int k = 0; k < 2; ++k) dst[m][k] = *(const LAS bf16x8*)(lds + PG8_SA(b, h) + aoff + m * 2048 + k * 1024); } while (0)
; #define PG8_LDB(dst, b, h) do { _Pragma("unroll") for (int n = 0; n < 2; ++n) _Pragma("unroll") for (int k = 0; k < 2; ++k) dst[n][k] = *(const LAS bf16x8*)(lds + PG8_SB(b, h) + boff + n * 2048 + k * 1024); } while (0)
; #define PG8_MMA(ai, bj, At, Bt) do { __builtin_amdgcn_s_setprio(1); _Pragma("unroll") for (int m = 0; m < 4; ++m) _Pragma("unroll") for (int n = 0; n < 2; ++n) _Pragma("unroll") for (int k = 0; k < 2; ++k) \
;         acc[ai][bj][m][n] = __builtin_amdgcn_mfma_f32_16x16x32_bf16(Bt[n][k], At[m][k], acc[ai][bj][m][n], 0, 0, 0); __builtin_amdgcn_s_setprio(0); } while (0)
; #define PG8_WAIT_V(n) asm volatile("s_waitcnt vmcnt(" #n ")" ::: "memory")
; #define PG8_WAIT_L(n) asm volatile("s_waitcnt lgkmcnt(" #n ")" ::: "memory")
; #define PG8_BAR __builtin_amdgcn_s_barrier()
; #define PG8_SCHED __builtin_amdgcn_sched_barrier(0)
; template <class Epi, class Sched>
; __device__ __forceinline__ void gemm_phase(LAS unsigned char* lds, const int K, const Sched& S, const Epi& E) {
;     ...
;             const bool last = (t == nt - 2);
;             const char* a1 = cA + (size_t)(t + 1) * kstep;
;             const char* a2 = last ? nA : cA + (size_t)(t + 2) * kstep; const char* b2 = last ? nB : cB + (size_t)(t + 2) * kstep;
;             const char* a3 = a2 + kstep; const char* b3 = b2 + kstep;
;             PG8_LDB(B0, 0, 0); PG8_LDB(B1, 0, 1); PG8_SCHED; PG8_LDA(At, 0, 0); PG8_STAGE(PG8_SA(1, 1), a1 + hstep, voffA);
;             PG8_WAIT_V(8); PG8_WAIT_L(0); PG8_BAR; PG8_MMA(0, 0, At, B0); PG8_MMA(0, 1, At, B1); PG8_BAR; PG8_SCHED;
;             PG8_LDA(At, 0, 1); PG8_STAGE(PG8_SB(0, 0), b2, voffB); PG8_STAGE(PG8_SB(0, 1), b2 + hstep, voffB); PG8_STAGE(PG8_SA(0, 0), a2, voffA);
.LBB0_812:
	s_add_i32 s16, s15, 2
	s_add_u32 s50, s8, 0x100
	s_addc_u32 s51, s9, 0
	s_add_i32 s17, 0, 0x10000
	s_cmp_eq_u32 s12, s15
	s_cselect_b32 s55, s4, s51
	s_cselect_b32 s54, s5, s50
	s_cselect_b32 s53, s10, s14
	s_cselect_b32 s52, s11, s13
	s_add_i32 s15, 0, 0x14000
	v_add_u32_e32 v158, s17, v164
	v_add_u32_e32 v162, s15, v164
	ds_read_b128 v[146:149], v158
	ds_read_b128 v[150:153], v158 offset:1024
	ds_read_b128 v[154:157], v158 offset:2048
	ds_read_b128 v[158:161], v158 offset:3072
	ds_read_b128 v[184:187], v162
	ds_read_b128 v[188:191], v162 offset:1024
	ds_read_b128 v[192:195], v162 offset:2048
	ds_read_b128 v[196:199], v162 offset:3072
	v_lshl_add_u64 v[162:163], s[8:9], 0, v[142:143]
	s_add_i32 m0, s26, 0xc000
	ds_read_b128 v[200:203], v166
	ds_read_b128 v[204:207], v166 offset:1024
	ds_read_b128 v[208:211], v166 offset:2048
	ds_read_b128 v[212:215], v166 offset:3072
	ds_read_b128 v[216:219], v166 offset:4096
	ds_read_b128 v[220:223], v166 offset:5120
	ds_read_b128 v[224:227], v166 offset:6144
	ds_read_b128 v[228:231], v166 offset:7168
	global_load_lds_dwordx4 v[162:163], off
	v_lshl_add_u64 v[162:163], s[8:9], 0, v[144:145]
	s_add_i32 m0, s26, 0xe000
	s_nop 0
	global_load_lds_dwordx4 v[162:163], off
	s_waitcnt vmcnt(8)
	s_waitcnt lgkmcnt(0)
	s_setprio 1
	s_barrier
	v_mfma_f32_16x16x32_bf16 v[124:127], v[146:149], v[200:203], v[124:127]
	v_mfma_f32_16x16x32_bf16 v[92:95], v[154:157], v[200:203], v[92:95]
	v_mfma_f32_16x16x32_bf16 v[120:123], v[146:149], v[208:211], v[120:123]
	v_mfma_f32_16x16x32_bf16 v[88:91], v[154:157], v[208:211], v[88:91]
	v_mfma_f32_16x16x32_bf16 v[116:119], v[146:149], v[216:219], v[116:119]
	v_mfma_f32_16x16x32_bf16 v[84:87], v[154:157], v[216:219], v[84:87]
	v_mfma_f32_16x16x32_bf16 v[112:115], v[146:149], v[224:227], v[112:115]
	v_mfma_f32_16x16x32_bf16 v[80:83], v[154:157], v[224:227], v[80:83]
	v_mfma_f32_16x16x32_bf16 v[124:127], v[150:153], v[204:207], v[124:127]
	v_mfma_f32_16x16x32_bf16 v[92:95], v[158:161], v[204:207], v[92:95]
	v_mfma_f32_16x16x32_bf16 v[120:123], v[150:153], v[212:215], v[120:123]
	v_mfma_f32_16x16x32_bf16 v[88:91], v[158:161], v[212:215], v[88:91]
	v_mfma_f32_16x16x32_bf16 v[116:119], v[150:153], v[220:223], v[116:119]
	v_mfma_f32_16x16x32_bf16 v[84:87], v[158:161], v[220:223], v[84:87]
	v_mfma_f32_16x16x32_bf16 v[112:115], v[150:153], v[228:231], v[112:115]
	v_mfma_f32_16x16x32_bf16 v[80:83], v[158:161], v[228:231], v[80:83]
	s_setprio 0
	s_setprio 1
	v_mfma_f32_16x16x32_bf16 v[64:67], v[184:187], v[200:203], v[64:67]
	v_mfma_f32_16x16x32_bf16 v[40:43], v[192:195], v[200:203], v[40:43]
	v_mfma_f32_16x16x32_bf16 v[56:59], v[184:187], v[208:211], v[56:59]
	v_mfma_f32_16x16x32_bf16 v[32:35], v[192:195], v[208:211], v[32:35]
	v_mfma_f32_16x16x32_bf16 v[52:55], v[184:187], v[216:219], v[52:55]
	v_mfma_f32_16x16x32_bf16 v[24:27], v[192:195], v[216:219], v[24:27]
	v_mfma_f32_16x16x32_bf16 v[48:51], v[184:187], v[224:227], v[48:51]
	v_mfma_f32_16x16x32_bf16 v[16:19], v[192:195], v[224:227], v[16:19]
	v_mfma_f32_16x16x32_bf16 v[64:67], v[188:191], v[204:207], v[64:67]
	v_mfma_f32_16x16x32_bf16 v[40:43], v[196:199], v[204:207], v[40:43]
	v_mfma_f32_16x16x32_bf16 v[56:59], v[188:191], v[212:215], v[56:59]
	v_mfma_f32_16x16x32_bf16 v[32:35], v[196:199], v[212:215], v[32:35]
	v_mfma_f32_16x16x32_bf16 v[52:55], v[188:191], v[220:223], v[52:55]
	v_mfma_f32_16x16x32_bf16 v[24:27], v[196:199], v[220:223], v[24:27]
	v_mfma_f32_16x16x32_bf16 v[48:51], v[188:191], v[228:231], v[48:51]
	v_mfma_f32_16x16x32_bf16 v[16:19], v[196:199], v[228:231], v[16:19]
	s_barrier
	s_setprio 0
	s_add_i32 s8, s17, s3
	v_lshl_add_u64 v[162:163], s[52:53], 0, v[128:129]
	s_mov_b32 m0, s8
	ds_read_b128 v[200:203], v166 offset:16384
	ds_read_b128 v[204:207], v166 offset:17408
	ds_read_b128 v[208:211], v166 offset:18432
	ds_read_b128 v[212:215], v166 offset:19456
	ds_read_b128 v[216:219], v166 offset:20480
	ds_read_b128 v[220:223], v166 offset:21504
	ds_read_b128 v[224:227], v166 offset:22528
	ds_read_b128 v[228:231], v166 offset:23552
	global_load_lds_dwordx4 v[162:163], off
	s_add_i32 m0, s8, 0x2000
	s_add_u32 s8, s52, 0x50000
	v_lshl_add_u64 v[180:181], s[52:53], 0, v[138:139]
	s_addc_u32 s9, s53, 0
	s_add_i32 s15, s15, s3
	global_load_lds_dwordx4 v[180:181], off
	v_lshl_add_u64 v[182:183], s[8:9], 0, v[128:129]
	s_mov_b32 m0, s15
	v_lshl_add_u64 v[232:233], s[54:55], 0, v[138:139]
	global_load_lds_dwordx4 v[182:183], off
	v_lshl_add_u64 v[182:183], s[8:9], 0, v[138:139]
	s_add_i32 m0, s15, 0x2000
	s_nop 0
	global_load_lds_dwordx4 v[182:183], off
	v_lshl_add_u64 v[182:183], s[54:55], 0, v[128:129]
	s_mov_b32 m0, s26
	s_nop 0
	global_load_lds_dwordx4 v[182:183], off
	s_mov_b32 m0, s27
	s_nop 0
	global_load_lds_dwordx4 v[232:233], off
	s_waitcnt vmcnt(8)
	s_waitcnt lgkmcnt(0)
	s_setprio 1
	s_barrier
; #define PG8_STAGE(bufoff, gbase, voff) do { _Pragma("unroll") for (int _i = 0; _i < 2; ++_i) \
;         __builtin_amdgcn_global_load_lds((const unsigned*)((const char*)(gbase) + (voff)[_i]), (LAS unsigned*)(lds + (bufoff) + ldsw + _i * 8192), 16, 0, 0); } while (0)
; #define PG8_LDA(dst, b, h) do { _Pragma("unroll") for (int m = 0; m < 4; ++m) _Pragma("unroll") for (int k = 0; k < 2; ++k) dst[m][k] = *(const LAS bf16x8*)(lds + PG8_SA(b, h) + aoff + m * 2048 + k * 1024); } while (0)
; #define PG8_LDB(dst, b, h) do { _Pragma("unroll") for (int n = 0; n < 2; ++n) _Pragma("unroll") for (int k = 0; k < 2; ++k) dst[n][k] = *(const LAS bf16x8*)(lds + PG8_SB(b, h) + boff + n * 2048 + k * 1024); } while (0)
; #define PG8_MMA(ai, bj, At, Bt) do { __builtin_amdgcn_s_setprio(1); _Pragma("unroll") for (int m = 0; m < 4; ++m) _Pragma("unroll") for (int n = 0; n < 2; ++n) _Pragma("unroll") for (int k = 0; k < 2; ++k) \
;         acc[ai][bj][m][n] = __builtin_amdgcn_mfma_f32_16x16x32_bf16(Bt[n][k], At[m][k], acc[ai][bj][m][n], 0, 0, 0); __builtin_amdgcn_s_setprio(0); } while (0)
; #define PG8_WAIT_V(n) asm volatile("s_waitcnt vmcnt(" #n ")" ::: "memory")
; #define PG8_WAIT_L(n) asm volatile("s_waitcnt lgkmcnt(" #n ")" ::: "memory")
; #define PG8_BAR __builtin_amdgcn_s_barrier()
; #define PG8_SCHED __builtin_amdgcn_sched_barrier(0)
; template <class Epi, class Sched>
; __device__ __forceinline__ void gemm_phase(LAS unsigned char* lds, const int K, const Sched& S, const Epi& E) {
;     ...
;             PG8_WAIT_V(8); PG8_WAIT_L(0); PG8_BAR; PG8_MMA(1, 0, At, B0); PG8_MMA(1, 1, At, B1); PG8_BAR; PG8_SCHED;
;             PG8_LDB(B0, 1, 0); PG8_LDB(B1, 1, 1); PG8_SCHED; PG8_LDA(At, 1, 0); PG8_STAGE(PG8_SA(0, 1), a2 + hstep, voffA);
;             PG8_WAIT_V(8); PG8_WAIT_L(0); PG8_BAR; PG8_MMA(0, 0, At, B0); PG8_MMA(0, 1, At, B1); PG8_BAR; PG8_SCHED;
	v_mfma_f32_16x16x32_bf16 v[108:111], v[146:149], v[200:203], v[108:111]
	v_mfma_f32_16x16x32_bf16 v[76:79], v[154:157], v[200:203], v[76:79]
	v_mfma_f32_16x16x32_bf16 v[104:107], v[146:149], v[208:211], v[104:107]
	v_mfma_f32_16x16x32_bf16 v[72:75], v[154:157], v[208:211], v[72:75]
	v_mfma_f32_16x16x32_bf16 v[100:103], v[146:149], v[216:219], v[100:103]
	v_mfma_f32_16x16x32_bf16 v[68:71], v[154:157], v[216:219], v[68:71]
	v_mfma_f32_16x16x32_bf16 v[96:99], v[146:149], v[224:227], v[96:99]
	v_mfma_f32_16x16x32_bf16 v[60:63], v[154:157], v[224:227], v[60:63]
	v_mfma_f32_16x16x32_bf16 v[108:111], v[150:153], v[204:207], v[108:111]
	v_mfma_f32_16x16x32_bf16 v[76:79], v[158:161], v[204:207], v[76:79]
	v_mfma_f32_16x16x32_bf16 v[104:107], v[150:153], v[212:215], v[104:107]
	v_mfma_f32_16x16x32_bf16 v[72:75], v[158:161], v[212:215], v[72:75]
	v_mfma_f32_16x16x32_bf16 v[100:103], v[150:153], v[220:223], v[100:103]
	v_mfma_f32_16x16x32_bf16 v[68:71], v[158:161], v[220:223], v[68:71]
	v_mfma_f32_16x16x32_bf16 v[96:99], v[150:153], v[228:231], v[96:99]
	v_mfma_f32_16x16x32_bf16 v[60:63], v[158:161], v[228:231], v[60:63]
	s_setprio 0
	s_setprio 1
	v_mfma_f32_16x16x32_bf16 v[44:47], v[184:187], v[200:203], v[44:47]
	v_mfma_f32_16x16x32_bf16 v[12:15], v[192:195], v[200:203], v[12:15]
	v_mfma_f32_16x16x32_bf16 v[36:39], v[184:187], v[208:211], v[36:39]
	v_mfma_f32_16x16x32_bf16 v[8:11], v[192:195], v[208:211], v[8:11]
	v_mfma_f32_16x16x32_bf16 v[28:31], v[184:187], v[216:219], v[28:31]
	v_mfma_f32_16x16x32_bf16 v[4:7], v[192:195], v[216:219], v[4:7]
	v_mfma_f32_16x16x32_bf16 v[20:23], v[184:187], v[224:227], v[20:23]
	v_mfma_f32_16x16x32_bf16 v[0:3], v[192:195], v[224:227], v[0:3]
	v_mfma_f32_16x16x32_bf16 v[44:47], v[188:191], v[204:207], v[44:47]
	v_mfma_f32_16x16x32_bf16 v[12:15], v[196:199], v[204:207], v[12:15]
	v_mfma_f32_16x16x32_bf16 v[36:39], v[188:191], v[212:215], v[36:39]
	v_mfma_f32_16x16x32_bf16 v[8:11], v[196:199], v[212:215], v[8:11]
	v_mfma_f32_16x16x32_bf16 v[28:31], v[188:191], v[220:223], v[28:31]
	v_mfma_f32_16x16x32_bf16 v[4:7], v[196:199], v[220:223], v[4:7]
	v_mfma_f32_16x16x32_bf16 v[20:23], v[188:191], v[228:231], v[20:23]
	v_mfma_f32_16x16x32_bf16 v[0:3], v[196:199], v[228:231], v[0:3]
	s_barrier
	s_setprio 0
	s_add_i32 s15, 0, 0x18000
	s_add_i32 s17, 0, 0x1c000
	v_add_u32_e32 v158, s15, v164
	v_add_u32_e32 v167, s17, v164
	ds_read_b128 v[146:149], v158
	ds_read_b128 v[150:153], v158 offset:1024
	ds_read_b128 v[154:157], v158 offset:2048
	ds_read_b128 v[158:161], v158 offset:3072
	ds_read_b128 v[184:187], v167
	ds_read_b128 v[188:191], v167 offset:1024
	ds_read_b128 v[192:195], v167 offset:2048
	ds_read_b128 v[196:199], v167 offset:3072
	s_add_u32 s8, s54, 0x50000
	s_addc_u32 s9, s55, 0
	s_mov_b32 m0, s56
	v_lshl_add_u64 v[234:235], s[8:9], 0, v[128:129]
	ds_read_b128 v[200:203], v166 offset:32768
	ds_read_b128 v[204:207], v166 offset:33792
	ds_read_b128 v[208:211], v166 offset:34816
	ds_read_b128 v[212:215], v166 offset:35840
	ds_read_b128 v[216:219], v166 offset:36864
	ds_read_b128 v[220:223], v166 offset:37888
	ds_read_b128 v[224:227], v166 offset:38912
	ds_read_b128 v[228:231], v166 offset:39936
	global_load_lds_dwordx4 v[234:235], off
	v_lshl_add_u64 v[234:235], s[8:9], 0, v[138:139]
	s_mov_b32 m0, s57
	s_nop 0
	global_load_lds_dwordx4 v[234:235], off
	s_waitcnt vmcnt(8)
	s_waitcnt lgkmcnt(0)
	s_setprio 1
	s_barrier
	v_mfma_f32_16x16x32_bf16 v[124:127], v[146:149], v[200:203], v[124:127]
	v_mfma_f32_16x16x32_bf16 v[92:95], v[154:157], v[200:203], v[92:95]
	v_mfma_f32_16x16x32_bf16 v[120:123], v[146:149], v[208:211], v[120:123]
	v_mfma_f32_16x16x32_bf16 v[88:91], v[154:157], v[208:211], v[88:91]
	v_mfma_f32_16x16x32_bf16 v[116:119], v[146:149], v[216:219], v[116:119]
	v_mfma_f32_16x16x32_bf16 v[84:87], v[154:157], v[216:219], v[84:87]
	v_mfma_f32_16x16x32_bf16 v[112:115], v[146:149], v[224:227], v[112:115]
	v_mfma_f32_16x16x32_bf16 v[80:83], v[154:157], v[224:227], v[80:83]
	v_mfma_f32_16x16x32_bf16 v[124:127], v[150:153], v[204:207], v[124:127]
	v_mfma_f32_16x16x32_bf16 v[92:95], v[158:161], v[204:207], v[92:95]
	v_mfma_f32_16x16x32_bf16 v[120:123], v[150:153], v[212:215], v[120:123]
	v_mfma_f32_16x16x32_bf16 v[88:91], v[158:161], v[212:215], v[88:91]
	v_mfma_f32_16x16x32_bf16 v[116:119], v[150:153], v[220:223], v[116:119]
	v_mfma_f32_16x16x32_bf16 v[84:87], v[158:161], v[220:223], v[84:87]
	v_mfma_f32_16x16x32_bf16 v[112:115], v[150:153], v[228:231], v[112:115]
	v_mfma_f32_16x16x32_bf16 v[80:83], v[158:161], v[228:231], v[80:83]
	s_setprio 0
	s_setprio 1
	v_mfma_f32_16x16x32_bf16 v[64:67], v[184:187], v[200:203], v[64:67]
	v_mfma_f32_16x16x32_bf16 v[40:43], v[192:195], v[200:203], v[40:43]
	v_mfma_f32_16x16x32_bf16 v[56:59], v[184:187], v[208:211], v[56:59]
	v_mfma_f32_16x16x32_bf16 v[32:35], v[192:195], v[208:211], v[32:35]
	v_mfma_f32_16x16x32_bf16 v[52:55], v[184:187], v[216:219], v[52:55]
	v_mfma_f32_16x16x32_bf16 v[24:27], v[192:195], v[216:219], v[24:27]
	v_mfma_f32_16x16x32_bf16 v[48:51], v[184:187], v[224:227], v[48:51]
	v_mfma_f32_16x16x32_bf16 v[16:19], v[192:195], v[224:227], v[16:19]
	v_mfma_f32_16x16x32_bf16 v[64:67], v[188:191], v[204:207], v[64:67]
	v_mfma_f32_16x16x32_bf16 v[40:43], v[196:199], v[204:207], v[40:43]
	v_mfma_f32_16x16x32_bf16 v[56:59], v[188:191], v[212:215], v[56:59]
	v_mfma_f32_16x16x32_bf16 v[32:35], v[196:199], v[212:215], v[32:35]
	v_mfma_f32_16x16x32_bf16 v[52:55], v[188:191], v[220:223], v[52:55]
	v_mfma_f32_16x16x32_bf16 v[24:27], v[196:199], v[220:223], v[24:27]
	v_mfma_f32_16x16x32_bf16 v[48:51], v[188:191], v[228:231], v[48:51]
	v_mfma_f32_16x16x32_bf16 v[16:19], v[196:199], v[228:231], v[16:19]
	s_barrier
; #define PG8_STAGE(bufoff, gbase, voff) do { _Pragma("unroll") for (int _i = 0; _i < 2; ++_i) \
;         __builtin_amdgcn_global_load_lds((const unsigned*)((const char*)(gbase) + (voff)[_i]), (LAS unsigned*)(lds + (bufoff) + ldsw + _i * 8192), 16, 0, 0); } while (0)
; #define PG8_LDA(dst, b, h) do { _Pragma("unroll") for (int m = 0; m < 4; ++m) _Pragma("unroll") for (int k = 0; k < 2; ++k) dst[m][k] = *(const LAS bf16x8*)(lds + PG8_SA(b, h) + aoff + m * 2048 + k * 1024); } while (0)
; #define PG8_MMA(ai, bj, At, Bt) do { __builtin_amdgcn_s_setprio(1); _Pragma("unroll") for (int m = 0; m < 4; ++m) _Pragma("unroll") for (int n = 0; n < 2; ++n) _Pragma("unroll") for (int k = 0; k < 2; ++k) \
;         acc[ai][bj][m][n] = __builtin_amdgcn_mfma_f32_16x16x32_bf16(Bt[n][k], At[m][k], acc[ai][bj][m][n], 0, 0, 0); __builtin_amdgcn_s_setprio(0); } while (0)
; #define PG8_WAIT_V(n) asm volatile("s_waitcnt vmcnt(" #n ")" ::: "memory")
; #define PG8_WAIT_L(n) asm volatile("s_waitcnt lgkmcnt(" #n ")" ::: "memory")
; #define PG8_BAR __builtin_amdgcn_s_barrier()
; #define PG8_SCHED __builtin_amdgcn_sched_barrier(0)
; template <class Epi, class Sched>
; __device__ __forceinline__ void gemm_phase(LAS unsigned char* lds, const int K, const Sched& S, const Epi& E) {
;     ...
;             PG8_LDA(At, 1, 1); PG8_STAGE(PG8_SB(1, 0), b3, voffB); PG8_STAGE(PG8_SB(1, 1), b3 + hstep, voffB); PG8_STAGE(PG8_SA(1, 0), a3, voffA);
;             PG8_WAIT_V(8); PG8_WAIT_L(0); PG8_BAR; PG8_MMA(1, 0, At, B0); PG8_MMA(1, 1, At, B1); PG8_BAR; PG8_SCHED;
;         }
;         if (wr == 0) PG8_BAR;
	s_setprio 0
	s_add_i32 s8, s15, s3
	v_lshl_add_u64 v[162:163], v[162:163], 0, s[36:37]
	s_mov_b32 m0, s8
	ds_read_b128 v[200:203], v166 offset:49152
	ds_read_b128 v[204:207], v166 offset:50176
	ds_read_b128 v[208:211], v166 offset:51200
	ds_read_b128 v[212:215], v166 offset:52224
	ds_read_b128 v[216:219], v166 offset:53248
	ds_read_b128 v[220:223], v166 offset:54272
	ds_read_b128 v[224:227], v166 offset:55296
	ds_read_b128 v[228:231], v166 offset:56320
	global_load_lds_dwordx4 v[162:163], off
	s_add_i32 m0, s8, 0x2000
	s_add_u32 s8, s52, 0x50080
	v_lshl_add_u64 v[162:163], v[180:181], 0, s[36:37]
	s_addc_u32 s9, s53, 0
	s_add_i32 s15, s17, s3
	global_load_lds_dwordx4 v[162:163], off
	v_lshl_add_u64 v[162:163], s[8:9], 0, v[128:129]
	s_mov_b32 m0, s15
	s_nop 0
	global_load_lds_dwordx4 v[162:163], off
	v_lshl_add_u64 v[162:163], s[8:9], 0, v[138:139]
	s_add_i32 m0, s15, 0x2000
	s_nop 0
	global_load_lds_dwordx4 v[162:163], off
	v_lshl_add_u64 v[162:163], v[182:183], 0, s[36:37]
	s_mov_b32 m0, s58
	s_nop 0
	global_load_lds_dwordx4 v[162:163], off
	v_lshl_add_u64 v[162:163], v[232:233], 0, s[36:37]
	s_mov_b32 m0, s59
	s_nop 0
	global_load_lds_dwordx4 v[162:163], off
	s_waitcnt vmcnt(8)
	s_waitcnt lgkmcnt(0)
	s_setprio 1
	s_barrier
	v_mfma_f32_16x16x32_bf16 v[108:111], v[146:149], v[200:203], v[108:111]
	v_mfma_f32_16x16x32_bf16 v[76:79], v[154:157], v[200:203], v[76:79]
	v_mfma_f32_16x16x32_bf16 v[104:107], v[146:149], v[208:211], v[104:107]
	v_mfma_f32_16x16x32_bf16 v[72:75], v[154:157], v[208:211], v[72:75]
	v_mfma_f32_16x16x32_bf16 v[100:103], v[146:149], v[216:219], v[100:103]
	v_mfma_f32_16x16x32_bf16 v[68:71], v[154:157], v[216:219], v[68:71]
	v_mfma_f32_16x16x32_bf16 v[96:99], v[146:149], v[224:227], v[96:99]
	v_mfma_f32_16x16x32_bf16 v[60:63], v[154:157], v[224:227], v[60:63]
	v_mfma_f32_16x16x32_bf16 v[108:111], v[150:153], v[204:207], v[108:111]
	v_mfma_f32_16x16x32_bf16 v[76:79], v[158:161], v[204:207], v[76:79]
	v_mfma_f32_16x16x32_bf16 v[104:107], v[150:153], v[212:215], v[104:107]
	v_mfma_f32_16x16x32_bf16 v[72:75], v[158:161], v[212:215], v[72:75]
	v_mfma_f32_16x16x32_bf16 v[100:103], v[150:153], v[220:223], v[100:103]
	v_mfma_f32_16x16x32_bf16 v[68:71], v[158:161], v[220:223], v[68:71]
	v_mfma_f32_16x16x32_bf16 v[96:99], v[150:153], v[228:231], v[96:99]
	v_mfma_f32_16x16x32_bf16 v[60:63], v[158:161], v[228:231], v[60:63]
	s_setprio 0
	s_setprio 1
	v_mfma_f32_16x16x32_bf16 v[44:47], v[184:187], v[200:203], v[44:47]
	v_mfma_f32_16x16x32_bf16 v[12:15], v[192:195], v[200:203], v[12:15]
	v_mfma_f32_16x16x32_bf16 v[36:39], v[184:187], v[208:211], v[36:39]
	v_mfma_f32_16x16x32_bf16 v[8:11], v[192:195], v[208:211], v[8:11]
	v_mfma_f32_16x16x32_bf16 v[28:31], v[184:187], v[216:219], v[28:31]
	v_mfma_f32_16x16x32_bf16 v[4:7], v[192:195], v[216:219], v[4:7]
	v_mfma_f32_16x16x32_bf16 v[20:23], v[184:187], v[224:227], v[20:23]
	v_mfma_f32_16x16x32_bf16 v[0:3], v[192:195], v[224:227], v[0:3]
	v_mfma_f32_16x16x32_bf16 v[44:47], v[188:191], v[204:207], v[44:47]
	v_mfma_f32_16x16x32_bf16 v[12:15], v[196:199], v[204:207], v[12:15]
	v_mfma_f32_16x16x32_bf16 v[36:39], v[188:191], v[212:215], v[36:39]
	v_mfma_f32_16x16x32_bf16 v[8:11], v[196:199], v[212:215], v[8:11]
	v_mfma_f32_16x16x32_bf16 v[28:31], v[188:191], v[220:223], v[28:31]
	v_mfma_f32_16x16x32_bf16 v[4:7], v[196:199], v[220:223], v[4:7]
	v_mfma_f32_16x16x32_bf16 v[20:23], v[188:191], v[228:231], v[20:23]
	v_mfma_f32_16x16x32_bf16 v[0:3], v[196:199], v[228:231], v[0:3]
	s_barrier
	s_setprio 0
	s_add_u32 s13, s13, 0x100
	s_addc_u32 s14, s14, 0
	s_cmp_ge_i32 s16, s2
	s_mov_b64 s[8:9], s[50:51]
	s_mov_b32 s15, s16
	s_cbranch_scc0 .LBB0_812
	s_and_b64 vcc, exec, s[40:41]
	s_cbranch_vccz .LBB0_815
	s_barrier

; #define PG8_STAGE(bufoff, gbase, voff) do { _Pragma("unroll") for (int _i = 0; _i < 2; ++_i) \
;         __builtin_amdgcn_global_load_lds((const unsigned*)((const char*)(gbase) + (voff)[_i]), (LAS unsigned*)(lds + (bufoff) + ldsw + _i * 8192), 16, 0, 0); } while (0)
; #define PG8_LDA(dst, b, h) do { _Pragma("unroll") for (int m = 0; m < 4; ++m) _Pragma("unroll") for (int k = 0; k < 2; ++k) dst[m][k] = *(const LAS bf16x8*)(lds + PG8_SA(b, h) + aoff + m * 2048 + k * 1024); } while (0)
; #define PG8_LDB(dst, b, h) do { _Pragma("unroll") for (int n = 0; n < 2; ++n) _Pragma("unroll") for (int k = 0; k < 2; ++k) dst[n][k] = *(const LAS bf16x8*)(lds + PG8_SB(b, h) + boff + n * 2048 + k * 1024); } while (0)
; #define PG8_MMA(ai, bj, At, Bt) do { __builtin_amdgcn_s_setprio(1); _Pragma("unroll") for (int m = 0; m < 4; ++m) _Pragma("unroll") for (int n = 0; n < 2; ++n) _Pragma("unroll") for (int k = 0; k < 2; ++k) \
;         acc[ai][bj][m][n] = __builtin_amdgcn_mfma_f32_16x16x32_bf16(Bt[n][k], At[m][k], acc[ai][bj][m][n], 0, 0, 0); __builtin_amdgcn_s_setprio(0); } while (0)
; #define PG8_WAIT_V(n) asm volatile("s_waitcnt vmcnt(" #n ")" ::: "memory")
; #define PG8_WAIT_L(n) asm volatile("s_waitcnt lgkmcnt(" #n ")" ::: "memory")
; #define PG8_BAR __builtin_amdgcn_s_barrier()
; #define PG8_SCHED __builtin_amdgcn_sched_barrier(0)
; template <class Epi, class Sched>
; __device__ __forceinline__ void gemm_phase(LAS unsigned char* lds, const int K, const Sched& S, const Epi& E) {
;     ...
;             const bool last = (t == nt - 2);
;             const char* a1 = cA + (size_t)(t + 1) * kstep;
;             const char* a2 = last ? nA : cA + (size_t)(t + 2) * kstep; const char* b2 = last ? nB : cB + (size_t)(t + 2) * kstep;
;             const char* a3 = a2 + kstep; const char* b3 = b2 + kstep;
;             PG8_LDB(B0, 0, 0); PG8_LDB(B1, 0, 1); PG8_SCHED; PG8_LDA(At, 0, 0); PG8_STAGE(PG8_SA(1, 1), a1 + hstep, voffA);
;             PG8_WAIT_V(8); PG8_WAIT_L(0); PG8_BAR; PG8_MMA(0, 0, At, B0); PG8_MMA(0, 1, At, B1); PG8_BAR; PG8_SCHED;
;             PG8_LDA(At, 0, 1); PG8_STAGE(PG8_SB(0, 0), b2, voffB); PG8_STAGE(PG8_SB(0, 1), b2 + hstep, voffB); PG8_STAGE(PG8_SA(0, 0), a2, voffA);
.LBB0_963:
	s_add_u32 s5, s56, 0xfffc0080
	s_addc_u32 s9, s57, -1
	s_add_i32 s10, 0, 0x10000
	s_cmp_eq_u32 s4, 12
	s_cselect_b32 s61, s53, s9
	s_cselect_b32 s60, s52, s5
	v_add_u32_e32 v150, s10, v153
	s_cselect_b32 s59, s55, s2
	s_cselect_b32 s58, s54, s1
	s_add_i32 s5, 0, 0x14000
	ds_read_b128 v[156:159], v150
	ds_read_b128 v[160:163], v150 offset:1024
	ds_read_b128 v[164:167], v150 offset:2048
	ds_read_b128 v[180:183], v150 offset:3072
	v_add_u32_e32 v150, s5, v153
	ds_read_b128 v[184:187], v150
	ds_read_b128 v[188:191], v150 offset:1024
	ds_read_b128 v[192:195], v150 offset:2048
	ds_read_b128 v[196:199], v150 offset:3072
	v_lshl_add_u64 v[150:151], s[56:57], 0, v[146:147]
	s_add_i32 m0, s66, 0xc000
	ds_read_b128 v[200:203], v154
	ds_read_b128 v[204:207], v154 offset:1024
	ds_read_b128 v[208:211], v154 offset:2048
	ds_read_b128 v[212:215], v154 offset:3072
	ds_read_b128 v[216:219], v154 offset:4096
	ds_read_b128 v[220:223], v154 offset:5120
	ds_read_b128 v[224:227], v154 offset:6144
	ds_read_b128 v[228:231], v154 offset:7168
	global_load_lds_dwordx4 v[150:151], off
	v_lshl_add_u64 v[150:151], s[56:57], 0, v[148:149]
	s_add_i32 m0, s66, 0xe000
	s_nop 0
	global_load_lds_dwordx4 v[150:151], off
	s_waitcnt vmcnt(8)
	s_waitcnt lgkmcnt(0)
	s_setprio 1
	s_barrier
	v_mfma_f32_16x16x32_bf16 v[124:127], v[156:159], v[200:203], v[124:127]
	v_mfma_f32_16x16x32_bf16 v[116:119], v[164:167], v[200:203], v[116:119]
	v_mfma_f32_16x16x32_bf16 v[108:111], v[156:159], v[208:211], v[108:111]
	v_mfma_f32_16x16x32_bf16 v[100:103], v[164:167], v[208:211], v[100:103]
	v_mfma_f32_16x16x32_bf16 v[92:95], v[156:159], v[216:219], v[92:95]
	v_mfma_f32_16x16x32_bf16 v[84:87], v[164:167], v[216:219], v[84:87]
	v_mfma_f32_16x16x32_bf16 v[76:79], v[156:159], v[224:227], v[76:79]
	v_mfma_f32_16x16x32_bf16 v[68:71], v[164:167], v[224:227], v[68:71]
	v_mfma_f32_16x16x32_bf16 v[124:127], v[160:163], v[204:207], v[124:127]
	v_mfma_f32_16x16x32_bf16 v[116:119], v[180:183], v[204:207], v[116:119]
	v_mfma_f32_16x16x32_bf16 v[108:111], v[160:163], v[212:215], v[108:111]
	v_mfma_f32_16x16x32_bf16 v[100:103], v[180:183], v[212:215], v[100:103]
	v_mfma_f32_16x16x32_bf16 v[92:95], v[160:163], v[220:223], v[92:95]
	v_mfma_f32_16x16x32_bf16 v[84:87], v[180:183], v[220:223], v[84:87]
	v_mfma_f32_16x16x32_bf16 v[76:79], v[160:163], v[228:231], v[76:79]
	v_mfma_f32_16x16x32_bf16 v[68:71], v[180:183], v[228:231], v[68:71]
	s_setprio 0
	s_setprio 1
	v_mfma_f32_16x16x32_bf16 v[120:123], v[184:187], v[200:203], v[120:123]
	v_mfma_f32_16x16x32_bf16 v[112:115], v[192:195], v[200:203], v[112:115]
	v_mfma_f32_16x16x32_bf16 v[104:107], v[184:187], v[208:211], v[104:107]
	v_mfma_f32_16x16x32_bf16 v[96:99], v[192:195], v[208:211], v[96:99]
	v_mfma_f32_16x16x32_bf16 v[88:91], v[184:187], v[216:219], v[88:91]
	v_mfma_f32_16x16x32_bf16 v[80:83], v[192:195], v[216:219], v[80:83]
	v_mfma_f32_16x16x32_bf16 v[72:75], v[184:187], v[224:227], v[72:75]
	v_mfma_f32_16x16x32_bf16 v[64:67], v[192:195], v[224:227], v[64:67]
	v_mfma_f32_16x16x32_bf16 v[120:123], v[188:191], v[204:207], v[120:123]
	v_mfma_f32_16x16x32_bf16 v[112:115], v[196:199], v[204:207], v[112:115]
	v_mfma_f32_16x16x32_bf16 v[104:107], v[188:191], v[212:215], v[104:107]
	v_mfma_f32_16x16x32_bf16 v[96:99], v[196:199], v[212:215], v[96:99]
	v_mfma_f32_16x16x32_bf16 v[88:91], v[188:191], v[220:223], v[88:91]
	v_mfma_f32_16x16x32_bf16 v[80:83], v[196:199], v[220:223], v[80:83]
	v_mfma_f32_16x16x32_bf16 v[72:75], v[188:191], v[228:231], v[72:75]
	v_mfma_f32_16x16x32_bf16 v[64:67], v[196:199], v[228:231], v[64:67]
	s_barrier
	s_setprio 0
	s_add_i32 s9, s10, s63
	v_lshl_add_u64 v[150:151], s[58:59], 0, v[142:143]
	s_mov_b32 m0, s9
	ds_read_b128 v[200:203], v154 offset:16384
	ds_read_b128 v[204:207], v154 offset:17408
	ds_read_b128 v[208:211], v154 offset:18432
	ds_read_b128 v[212:215], v154 offset:19456
	ds_read_b128 v[216:219], v154 offset:20480
	ds_read_b128 v[220:223], v154 offset:21504
	ds_read_b128 v[224:227], v154 offset:22528
	ds_read_b128 v[228:231], v154 offset:23552
	global_load_lds_dwordx4 v[150:151], off
	s_add_i32 m0, s9, 0x2000
	s_add_u32 s10, s58, 0x40000
	v_lshl_add_u64 v[232:233], s[58:59], 0, v[138:139]
	s_addc_u32 s11, s59, 0
	s_add_i32 s5, s5, s63
	global_load_lds_dwordx4 v[232:233], off
	v_lshl_add_u64 v[234:235], s[10:11], 0, v[142:143]
	s_mov_b32 m0, s5
	v_lshl_add_u64 v[236:237], s[60:61], 0, v[140:141]
	global_load_lds_dwordx4 v[234:235], off
	v_lshl_add_u64 v[234:235], s[10:11], 0, v[138:139]
	s_add_i32 m0, s5, 0x2000
	s_nop 0
	global_load_lds_dwordx4 v[234:235], off
	v_lshl_add_u64 v[234:235], s[60:61], 0, v[144:145]
	s_mov_b32 m0, s66
	s_nop 0
	global_load_lds_dwordx4 v[234:235], off
	s_mov_b32 m0, s67
	s_nop 0
	global_load_lds_dwordx4 v[236:237], off
	s_waitcnt vmcnt(8)
	s_waitcnt lgkmcnt(0)
	s_setprio 1
	s_barrier
; #define PG8_STAGE(bufoff, gbase, voff) do { _Pragma("unroll") for (int _i = 0; _i < 2; ++_i) \
;         __builtin_amdgcn_global_load_lds((const unsigned*)((const char*)(gbase) + (voff)[_i]), (LAS unsigned*)(lds + (bufoff) + ldsw + _i * 8192), 16, 0, 0); } while (0)
; #define PG8_LDA(dst, b, h) do { _Pragma("unroll") for (int m = 0; m < 4; ++m) _Pragma("unroll") for (int k = 0; k < 2; ++k) dst[m][k] = *(const LAS bf16x8*)(lds + PG8_SA(b, h) + aoff + m * 2048 + k * 1024); } while (0)
; #define PG8_LDB(dst, b, h) do { _Pragma("unroll") for (int n = 0; n < 2; ++n) _Pragma("unroll") for (int k = 0; k < 2; ++k) dst[n][k] = *(const LAS bf16x8*)(lds + PG8_SB(b, h) + boff + n * 2048 + k * 1024); } while (0)
; #define PG8_MMA(ai, bj, At, Bt) do { __builtin_amdgcn_s_setprio(1); _Pragma("unroll") for (int m = 0; m < 4; ++m) _Pragma("unroll") for (int n = 0; n < 2; ++n) _Pragma("unroll") for (int k = 0; k < 2; ++k) \
;         acc[ai][bj][m][n] = __builtin_amdgcn_mfma_f32_16x16x32_bf16(Bt[n][k], At[m][k], acc[ai][bj][m][n], 0, 0, 0); __builtin_amdgcn_s_setprio(0); } while (0)
; #define PG8_WAIT_V(n) asm volatile("s_waitcnt vmcnt(" #n ")" ::: "memory")
; #define PG8_WAIT_L(n) asm volatile("s_waitcnt lgkmcnt(" #n ")" ::: "memory")
; #define PG8_BAR __builtin_amdgcn_s_barrier()
; #define PG8_SCHED __builtin_amdgcn_sched_barrier(0)
; template <class Epi, class Sched>
; __device__ __forceinline__ void gemm_phase(LAS unsigned char* lds, const int K, const Sched& S, const Epi& E) {
;     ...
;             PG8_WAIT_V(8); PG8_WAIT_L(0); PG8_BAR; PG8_MMA(1, 0, At, B0); PG8_MMA(1, 1, At, B1); PG8_BAR; PG8_SCHED;
;             PG8_LDB(B0, 1, 0); PG8_LDB(B1, 1, 1); PG8_SCHED; PG8_LDA(At, 1, 0); PG8_STAGE(PG8_SA(0, 1), a2 + hstep, voffA);
;             PG8_WAIT_V(8); PG8_WAIT_L(0); PG8_BAR; PG8_MMA(0, 0, At, B0); PG8_MMA(0, 1, At, B1); PG8_BAR; PG8_SCHED;
	v_mfma_f32_16x16x32_bf16 v[60:63], v[156:159], v[200:203], v[60:63]
	v_mfma_f32_16x16x32_bf16 v[52:55], v[164:167], v[200:203], v[52:55]
	v_mfma_f32_16x16x32_bf16 v[44:47], v[156:159], v[208:211], v[44:47]
	v_mfma_f32_16x16x32_bf16 v[36:39], v[164:167], v[208:211], v[36:39]
	v_mfma_f32_16x16x32_bf16 v[28:31], v[156:159], v[216:219], v[28:31]
	v_mfma_f32_16x16x32_bf16 v[20:23], v[164:167], v[216:219], v[20:23]
	v_mfma_f32_16x16x32_bf16 v[12:15], v[156:159], v[224:227], v[12:15]
	v_mfma_f32_16x16x32_bf16 v[4:7], v[164:167], v[224:227], v[4:7]
	v_mfma_f32_16x16x32_bf16 v[60:63], v[160:163], v[204:207], v[60:63]
	v_mfma_f32_16x16x32_bf16 v[52:55], v[180:183], v[204:207], v[52:55]
	v_mfma_f32_16x16x32_bf16 v[44:47], v[160:163], v[212:215], v[44:47]
	v_mfma_f32_16x16x32_bf16 v[36:39], v[180:183], v[212:215], v[36:39]
	v_mfma_f32_16x16x32_bf16 v[28:31], v[160:163], v[220:223], v[28:31]
	v_mfma_f32_16x16x32_bf16 v[20:23], v[180:183], v[220:223], v[20:23]
	v_mfma_f32_16x16x32_bf16 v[12:15], v[160:163], v[228:231], v[12:15]
	v_mfma_f32_16x16x32_bf16 v[4:7], v[180:183], v[228:231], v[4:7]
	s_setprio 0
	s_setprio 1
	v_mfma_f32_16x16x32_bf16 v[56:59], v[184:187], v[200:203], v[56:59]
	v_mfma_f32_16x16x32_bf16 v[48:51], v[192:195], v[200:203], v[48:51]
	v_mfma_f32_16x16x32_bf16 v[40:43], v[184:187], v[208:211], v[40:43]
	v_mfma_f32_16x16x32_bf16 v[32:35], v[192:195], v[208:211], v[32:35]
	v_mfma_f32_16x16x32_bf16 v[24:27], v[184:187], v[216:219], v[24:27]
	v_mfma_f32_16x16x32_bf16 v[16:19], v[192:195], v[216:219], v[16:19]
	v_mfma_f32_16x16x32_bf16 v[8:11], v[184:187], v[224:227], v[8:11]
	v_mfma_f32_16x16x32_bf16 v[0:3], v[192:195], v[224:227], v[0:3]
	v_mfma_f32_16x16x32_bf16 v[56:59], v[188:191], v[204:207], v[56:59]
	v_mfma_f32_16x16x32_bf16 v[48:51], v[196:199], v[204:207], v[48:51]
	v_mfma_f32_16x16x32_bf16 v[40:43], v[188:191], v[212:215], v[40:43]
	v_mfma_f32_16x16x32_bf16 v[32:35], v[196:199], v[212:215], v[32:35]
	v_mfma_f32_16x16x32_bf16 v[24:27], v[188:191], v[220:223], v[24:27]
	v_mfma_f32_16x16x32_bf16 v[16:19], v[196:199], v[220:223], v[16:19]
	v_mfma_f32_16x16x32_bf16 v[8:11], v[188:191], v[228:231], v[8:11]
	v_mfma_f32_16x16x32_bf16 v[0:3], v[196:199], v[228:231], v[0:3]
	s_barrier
	s_setprio 0
	s_add_i32 s5, 0, 0x18000
	v_add_u32_e32 v155, s5, v153
	s_add_i32 s9, 0, 0x1c000
	ds_read_b128 v[156:159], v155
	ds_read_b128 v[160:163], v155 offset:1024
	ds_read_b128 v[164:167], v155 offset:2048
	ds_read_b128 v[180:183], v155 offset:3072
	v_add_u32_e32 v155, s9, v153
	ds_read_b128 v[184:187], v155
	ds_read_b128 v[188:191], v155 offset:1024
	ds_read_b128 v[192:195], v155 offset:2048
	ds_read_b128 v[196:199], v155 offset:3072
	s_add_u32 s10, s60, 0x40000
	s_addc_u32 s11, s61, 0
	s_mov_b32 m0, s68
	v_lshl_add_u64 v[238:239], s[10:11], 0, v[144:145]
	ds_read_b128 v[200:203], v154 offset:32768
	ds_read_b128 v[204:207], v154 offset:33792
	ds_read_b128 v[208:211], v154 offset:34816
	ds_read_b128 v[212:215], v154 offset:35840
	ds_read_b128 v[216:219], v154 offset:36864
	ds_read_b128 v[220:223], v154 offset:37888
	ds_read_b128 v[224:227], v154 offset:38912
	ds_read_b128 v[228:231], v154 offset:39936
	global_load_lds_dwordx4 v[238:239], off
	v_lshl_add_u64 v[238:239], s[10:11], 0, v[140:141]
	s_mov_b32 m0, s69
	s_nop 0
	global_load_lds_dwordx4 v[238:239], off
	s_waitcnt vmcnt(8)
	s_waitcnt lgkmcnt(0)
	s_setprio 1
	s_barrier
	v_mfma_f32_16x16x32_bf16 v[124:127], v[156:159], v[200:203], v[124:127]
	v_mfma_f32_16x16x32_bf16 v[116:119], v[164:167], v[200:203], v[116:119]
	v_mfma_f32_16x16x32_bf16 v[108:111], v[156:159], v[208:211], v[108:111]
	v_mfma_f32_16x16x32_bf16 v[100:103], v[164:167], v[208:211], v[100:103]
	v_mfma_f32_16x16x32_bf16 v[92:95], v[156:159], v[216:219], v[92:95]
	v_mfma_f32_16x16x32_bf16 v[84:87], v[164:167], v[216:219], v[84:87]
	v_mfma_f32_16x16x32_bf16 v[76:79], v[156:159], v[224:227], v[76:79]
	v_mfma_f32_16x16x32_bf16 v[68:71], v[164:167], v[224:227], v[68:71]
	v_mfma_f32_16x16x32_bf16 v[124:127], v[160:163], v[204:207], v[124:127]
	v_mfma_f32_16x16x32_bf16 v[116:119], v[180:183], v[204:207], v[116:119]
	v_mfma_f32_16x16x32_bf16 v[108:111], v[160:163], v[212:215], v[108:111]
	v_mfma_f32_16x16x32_bf16 v[100:103], v[180:183], v[212:215], v[100:103]
	v_mfma_f32_16x16x32_bf16 v[92:95], v[160:163], v[220:223], v[92:95]
	v_mfma_f32_16x16x32_bf16 v[84:87], v[180:183], v[220:223], v[84:87]
	v_mfma_f32_16x16x32_bf16 v[76:79], v[160:163], v[228:231], v[76:79]
	v_mfma_f32_16x16x32_bf16 v[68:71], v[180:183], v[228:231], v[68:71]
	s_setprio 0
	s_setprio 1
	v_mfma_f32_16x16x32_bf16 v[120:123], v[184:187], v[200:203], v[120:123]
	v_mfma_f32_16x16x32_bf16 v[112:115], v[192:195], v[200:203], v[112:115]
	v_mfma_f32_16x16x32_bf16 v[104:107], v[184:187], v[208:211], v[104:107]
	v_mfma_f32_16x16x32_bf16 v[96:99], v[192:195], v[208:211], v[96:99]
	v_mfma_f32_16x16x32_bf16 v[88:91], v[184:187], v[216:219], v[88:91]
	v_mfma_f32_16x16x32_bf16 v[80:83], v[192:195], v[216:219], v[80:83]
	v_mfma_f32_16x16x32_bf16 v[72:75], v[184:187], v[224:227], v[72:75]
	v_mfma_f32_16x16x32_bf16 v[64:67], v[192:195], v[224:227], v[64:67]
	v_mfma_f32_16x16x32_bf16 v[120:123], v[188:191], v[204:207], v[120:123]
	v_mfma_f32_16x16x32_bf16 v[112:115], v[196:199], v[204:207], v[112:115]
	v_mfma_f32_16x16x32_bf16 v[104:107], v[188:191], v[212:215], v[104:107]
	v_mfma_f32_16x16x32_bf16 v[96:99], v[196:199], v[212:215], v[96:99]
	v_mfma_f32_16x16x32_bf16 v[88:91], v[188:191], v[220:223], v[88:91]
	v_mfma_f32_16x16x32_bf16 v[80:83], v[196:199], v[220:223], v[80:83]
	v_mfma_f32_16x16x32_bf16 v[72:75], v[188:191], v[228:231], v[72:75]
	v_mfma_f32_16x16x32_bf16 v[64:67], v[196:199], v[228:231], v[64:67]
	s_barrier
; #define PG8_STAGE(bufoff, gbase, voff) do { _Pragma("unroll") for (int _i = 0; _i < 2; ++_i) \
;         __builtin_amdgcn_global_load_lds((const unsigned*)((const char*)(gbase) + (voff)[_i]), (LAS unsigned*)(lds + (bufoff) + ldsw + _i * 8192), 16, 0, 0); } while (0)
; #define PG8_LDA(dst, b, h) do { _Pragma("unroll") for (int m = 0; m < 4; ++m) _Pragma("unroll") for (int k = 0; k < 2; ++k) dst[m][k] = *(const LAS bf16x8*)(lds + PG8_SA(b, h) + aoff + m * 2048 + k * 1024); } while (0)
; #define PG8_MMA(ai, bj, At, Bt) do { __builtin_amdgcn_s_setprio(1); _Pragma("unroll") for (int m = 0; m < 4; ++m) _Pragma("unroll") for (int n = 0; n < 2; ++n) _Pragma("unroll") for (int k = 0; k < 2; ++k) \
;         acc[ai][bj][m][n] = __builtin_amdgcn_mfma_f32_16x16x32_bf16(Bt[n][k], At[m][k], acc[ai][bj][m][n], 0, 0, 0); __builtin_amdgcn_s_setprio(0); } while (0)
; #define PG8_WAIT_V(n) asm volatile("s_waitcnt vmcnt(" #n ")" ::: "memory")
; #define PG8_WAIT_L(n) asm volatile("s_waitcnt lgkmcnt(" #n ")" ::: "memory")
; #define PG8_BAR __builtin_amdgcn_s_barrier()
; #define PG8_SCHED __builtin_amdgcn_sched_barrier(0)
; template <class Epi, class Sched>
; __device__ __forceinline__ void gemm_phase(LAS unsigned char* lds, const int K, const Sched& S, const Epi& E) {
;     ...
;             PG8_LDA(At, 1, 1); PG8_STAGE(PG8_SB(1, 0), b3, voffB); PG8_STAGE(PG8_SB(1, 1), b3 + hstep, voffB); PG8_STAGE(PG8_SA(1, 0), a3, voffA);
;             PG8_WAIT_V(8); PG8_WAIT_L(0); PG8_BAR; PG8_MMA(1, 0, At, B0); PG8_MMA(1, 1, At, B1); PG8_BAR; PG8_SCHED;
;         }
;         if (wr == 0) PG8_BAR;
	s_setprio 0
	s_add_i32 s5, s5, s63
	v_lshl_add_u64 v[150:151], v[150:151], 0, s[36:37]
	s_mov_b32 m0, s5
	ds_read_b128 v[200:203], v154 offset:49152
	ds_read_b128 v[204:207], v154 offset:50176
	ds_read_b128 v[208:211], v154 offset:51200
	ds_read_b128 v[212:215], v154 offset:52224
	ds_read_b128 v[216:219], v154 offset:53248
	ds_read_b128 v[220:223], v154 offset:54272
	ds_read_b128 v[224:227], v154 offset:55296
	ds_read_b128 v[228:231], v154 offset:56320
	global_load_lds_dwordx4 v[150:151], off
	s_add_i32 m0, s5, 0x2000
	s_add_u32 s10, s58, 0x40080
	v_lshl_add_u64 v[150:151], v[232:233], 0, s[36:37]
	s_addc_u32 s11, s59, 0
	s_add_i32 s5, s9, s63
	global_load_lds_dwordx4 v[150:151], off
	v_lshl_add_u64 v[150:151], s[10:11], 0, v[142:143]
	s_mov_b32 m0, s5
	s_nop 0
	global_load_lds_dwordx4 v[150:151], off
	v_lshl_add_u64 v[150:151], s[10:11], 0, v[138:139]
	s_add_i32 m0, s5, 0x2000
	s_nop 0
	global_load_lds_dwordx4 v[150:151], off
	v_lshl_add_u64 v[150:151], v[234:235], 0, s[36:37]
	s_mov_b32 m0, s70
	s_nop 0
	global_load_lds_dwordx4 v[150:151], off
	v_lshl_add_u64 v[150:151], v[236:237], 0, s[36:37]
	s_mov_b32 m0, s71
	s_nop 0
	global_load_lds_dwordx4 v[150:151], off
	s_waitcnt vmcnt(8)
	s_waitcnt lgkmcnt(0)
	s_setprio 1
	s_barrier
	v_mfma_f32_16x16x32_bf16 v[60:63], v[156:159], v[200:203], v[60:63]
	v_mfma_f32_16x16x32_bf16 v[52:55], v[164:167], v[200:203], v[52:55]
	v_mfma_f32_16x16x32_bf16 v[44:47], v[156:159], v[208:211], v[44:47]
	v_mfma_f32_16x16x32_bf16 v[36:39], v[164:167], v[208:211], v[36:39]
	v_mfma_f32_16x16x32_bf16 v[28:31], v[156:159], v[216:219], v[28:31]
	v_mfma_f32_16x16x32_bf16 v[20:23], v[164:167], v[216:219], v[20:23]
	v_mfma_f32_16x16x32_bf16 v[12:15], v[156:159], v[224:227], v[12:15]
	v_mfma_f32_16x16x32_bf16 v[4:7], v[164:167], v[224:227], v[4:7]
	v_mfma_f32_16x16x32_bf16 v[60:63], v[160:163], v[204:207], v[60:63]
	v_mfma_f32_16x16x32_bf16 v[52:55], v[180:183], v[204:207], v[52:55]
	v_mfma_f32_16x16x32_bf16 v[44:47], v[160:163], v[212:215], v[44:47]
	v_mfma_f32_16x16x32_bf16 v[36:39], v[180:183], v[212:215], v[36:39]
	v_mfma_f32_16x16x32_bf16 v[28:31], v[160:163], v[220:223], v[28:31]
	v_mfma_f32_16x16x32_bf16 v[20:23], v[180:183], v[220:223], v[20:23]
	v_mfma_f32_16x16x32_bf16 v[12:15], v[160:163], v[228:231], v[12:15]
	v_mfma_f32_16x16x32_bf16 v[4:7], v[180:183], v[228:231], v[4:7]
	s_setprio 0
	s_setprio 1
	v_mfma_f32_16x16x32_bf16 v[56:59], v[184:187], v[200:203], v[56:59]
	v_mfma_f32_16x16x32_bf16 v[48:51], v[192:195], v[200:203], v[48:51]
	v_mfma_f32_16x16x32_bf16 v[40:43], v[184:187], v[208:211], v[40:43]
	v_mfma_f32_16x16x32_bf16 v[32:35], v[192:195], v[208:211], v[32:35]
	v_mfma_f32_16x16x32_bf16 v[24:27], v[184:187], v[216:219], v[24:27]
	v_mfma_f32_16x16x32_bf16 v[16:19], v[192:195], v[216:219], v[16:19]
	v_mfma_f32_16x16x32_bf16 v[8:11], v[184:187], v[224:227], v[8:11]
	v_mfma_f32_16x16x32_bf16 v[0:3], v[192:195], v[224:227], v[0:3]
	v_mfma_f32_16x16x32_bf16 v[56:59], v[188:191], v[204:207], v[56:59]
	v_mfma_f32_16x16x32_bf16 v[48:51], v[196:199], v[204:207], v[48:51]
	v_mfma_f32_16x16x32_bf16 v[40:43], v[188:191], v[212:215], v[40:43]
	v_mfma_f32_16x16x32_bf16 v[32:35], v[196:199], v[212:215], v[32:35]
	v_mfma_f32_16x16x32_bf16 v[24:27], v[188:191], v[220:223], v[24:27]
	v_mfma_f32_16x16x32_bf16 v[16:19], v[196:199], v[220:223], v[16:19]
	v_mfma_f32_16x16x32_bf16 v[8:11], v[188:191], v[228:231], v[8:11]
	v_mfma_f32_16x16x32_bf16 v[0:3], v[196:199], v[228:231], v[0:3]
	s_barrier
	s_setprio 0
	s_add_i32 s4, s4, 2
	s_add_u32 s56, s56, 0x100
	s_addc_u32 s57, s57, 0
	s_add_u32 s1, s1, 0x100
	s_addc_u32 s2, s2, 0
	s_cmp_gt_u32 s4, 13
	s_cbranch_scc0 .LBB0_963
	s_and_b64 vcc, exec, s[46:47]
	s_cbranch_vccz .LBB0_966
	s_barrier

; #define PG8_STAGE(bufoff, gbase, voff) do { _Pragma("unroll") for (int _i = 0; _i < 2; ++_i) \
;         __builtin_amdgcn_global_load_lds((const unsigned*)((const char*)(gbase) + (voff)[_i]), (LAS unsigned*)(lds + (bufoff) + ldsw + _i * 8192), 16, 0, 0); } while (0)
; #define PG8_LDA(dst, b, h) do { _Pragma("unroll") for (int m = 0; m < 4; ++m) _Pragma("unroll") for (int k = 0; k < 2; ++k) dst[m][k] = *(const LAS bf16x8*)(lds + PG8_SA(b, h) + aoff + m * 2048 + k * 1024); } while (0)
; #define PG8_LDB(dst, b, h) do { _Pragma("unroll") for (int n = 0; n < 2; ++n) _Pragma("unroll") for (int k = 0; k < 2; ++k) dst[n][k] = *(const LAS bf16x8*)(lds + PG8_SB(b, h) + boff + n * 2048 + k * 1024); } while (0)
; #define PG8_MMA(ai, bj, At, Bt) do { __builtin_amdgcn_s_setprio(1); _Pragma("unroll") for (int m = 0; m < 4; ++m) _Pragma("unroll") for (int n = 0; n < 2; ++n) _Pragma("unroll") for (int k = 0; k < 2; ++k) \
;         acc[ai][bj][m][n] = __builtin_amdgcn_mfma_f32_16x16x32_bf16(Bt[n][k], At[m][k], acc[ai][bj][m][n], 0, 0, 0); __builtin_amdgcn_s_setprio(0); } while (0)
; #define PG8_WAIT_V(n) asm volatile("s_waitcnt vmcnt(" #n ")" ::: "memory")
; #define PG8_WAIT_L(n) asm volatile("s_waitcnt lgkmcnt(" #n ")" ::: "memory")
; #define PG8_BAR __builtin_amdgcn_s_barrier()
; #define PG8_SCHED __builtin_amdgcn_sched_barrier(0)
; template <class Epi, class Sched>
; __device__ __forceinline__ void gemm_phase(LAS unsigned char* lds, const int K, const Sched& S, const Epi& E) {
;     ...
;             const bool last = (t == nt - 2);
;             const char* a1 = cA + (size_t)(t + 1) * kstep;
;             const char* a2 = last ? nA : cA + (size_t)(t + 2) * kstep; const char* b2 = last ? nB : cB + (size_t)(t + 2) * kstep;
;             const char* a3 = a2 + kstep; const char* b3 = b2 + kstep;
;             PG8_LDB(B0, 0, 0); PG8_LDB(B1, 0, 1); PG8_SCHED; PG8_LDA(At, 0, 0); PG8_STAGE(PG8_SA(1, 1), a1 + hstep, voffA);
;             PG8_WAIT_V(8); PG8_WAIT_L(0); PG8_BAR; PG8_MMA(0, 0, At, B0); PG8_MMA(0, 1, At, B1); PG8_BAR; PG8_SCHED;
;             PG8_LDA(At, 0, 1); PG8_STAGE(PG8_SB(0, 0), b2, voffB); PG8_STAGE(PG8_SB(0, 1), b2 + hstep, voffB); PG8_STAGE(PG8_SA(0, 0), a2, voffA);
.LBB0_1073:
	s_add_i32 s13, s12, 2
	s_add_u32 s52, s8, 0x100
	s_addc_u32 s53, s9, 0
	s_add_i32 s14, 0, 0x10000
	s_cmp_eq_u32 s5, s12
	s_cselect_b32 s57, s0, s53
	s_cselect_b32 s56, s1, s52
	s_cselect_b32 s55, s2, s11
	s_cselect_b32 s54, s4, s10
	s_add_i32 s12, 0, 0x14000
	v_add_u32_e32 v158, s14, v164
	v_add_u32_e32 v162, s12, v164
	ds_read_b128 v[146:149], v158
	ds_read_b128 v[150:153], v158 offset:1024
	ds_read_b128 v[154:157], v158 offset:2048
	ds_read_b128 v[158:161], v158 offset:3072
	ds_read_b128 v[180:183], v162
	ds_read_b128 v[184:187], v162 offset:1024
	ds_read_b128 v[188:191], v162 offset:2048
	ds_read_b128 v[192:195], v162 offset:3072
	v_lshl_add_u64 v[162:163], s[8:9], 0, v[142:143]
	s_add_i32 m0, s61, 0xc000
	ds_read_b128 v[196:199], v166
	ds_read_b128 v[200:203], v166 offset:1024
	ds_read_b128 v[204:207], v166 offset:2048
	ds_read_b128 v[208:211], v166 offset:3072
	ds_read_b128 v[212:215], v166 offset:4096
	ds_read_b128 v[216:219], v166 offset:5120
	ds_read_b128 v[220:223], v166 offset:6144
	ds_read_b128 v[224:227], v166 offset:7168
	global_load_lds_dwordx4 v[162:163], off
	v_lshl_add_u64 v[162:163], s[8:9], 0, v[144:145]
	s_add_i32 m0, s61, 0xe000
	s_nop 0
	global_load_lds_dwordx4 v[162:163], off
	s_waitcnt vmcnt(8)
	s_waitcnt lgkmcnt(0)
	s_setprio 1
	s_barrier
	v_mfma_f32_16x16x32_bf16 v[124:127], v[146:149], v[196:199], v[124:127]
	v_mfma_f32_16x16x32_bf16 v[92:95], v[154:157], v[196:199], v[92:95]
	v_mfma_f32_16x16x32_bf16 v[120:123], v[146:149], v[204:207], v[120:123]
	v_mfma_f32_16x16x32_bf16 v[88:91], v[154:157], v[204:207], v[88:91]
	v_mfma_f32_16x16x32_bf16 v[116:119], v[146:149], v[212:215], v[116:119]
	v_mfma_f32_16x16x32_bf16 v[84:87], v[154:157], v[212:215], v[84:87]
	v_mfma_f32_16x16x32_bf16 v[112:115], v[146:149], v[220:223], v[112:115]
	v_mfma_f32_16x16x32_bf16 v[80:83], v[154:157], v[220:223], v[80:83]
	v_mfma_f32_16x16x32_bf16 v[124:127], v[150:153], v[200:203], v[124:127]
	v_mfma_f32_16x16x32_bf16 v[92:95], v[158:161], v[200:203], v[92:95]
	v_mfma_f32_16x16x32_bf16 v[120:123], v[150:153], v[208:211], v[120:123]
	v_mfma_f32_16x16x32_bf16 v[88:91], v[158:161], v[208:211], v[88:91]
	v_mfma_f32_16x16x32_bf16 v[116:119], v[150:153], v[216:219], v[116:119]
	v_mfma_f32_16x16x32_bf16 v[84:87], v[158:161], v[216:219], v[84:87]
	v_mfma_f32_16x16x32_bf16 v[112:115], v[150:153], v[224:227], v[112:115]
	v_mfma_f32_16x16x32_bf16 v[80:83], v[158:161], v[224:227], v[80:83]
	s_setprio 0
	s_setprio 1
	v_mfma_f32_16x16x32_bf16 v[60:63], v[180:183], v[196:199], v[60:63]
	v_mfma_f32_16x16x32_bf16 v[28:31], v[188:191], v[196:199], v[28:31]
	v_mfma_f32_16x16x32_bf16 v[56:59], v[180:183], v[204:207], v[56:59]
	v_mfma_f32_16x16x32_bf16 v[24:27], v[188:191], v[204:207], v[24:27]
	v_mfma_f32_16x16x32_bf16 v[52:55], v[180:183], v[212:215], v[52:55]
	v_mfma_f32_16x16x32_bf16 v[20:23], v[188:191], v[212:215], v[20:23]
	v_mfma_f32_16x16x32_bf16 v[48:51], v[180:183], v[220:223], v[48:51]
	v_mfma_f32_16x16x32_bf16 v[16:19], v[188:191], v[220:223], v[16:19]
	v_mfma_f32_16x16x32_bf16 v[60:63], v[184:187], v[200:203], v[60:63]
	v_mfma_f32_16x16x32_bf16 v[28:31], v[192:195], v[200:203], v[28:31]
	v_mfma_f32_16x16x32_bf16 v[56:59], v[184:187], v[208:211], v[56:59]
	v_mfma_f32_16x16x32_bf16 v[24:27], v[192:195], v[208:211], v[24:27]
	v_mfma_f32_16x16x32_bf16 v[52:55], v[184:187], v[216:219], v[52:55]
	v_mfma_f32_16x16x32_bf16 v[20:23], v[192:195], v[216:219], v[20:23]
	v_mfma_f32_16x16x32_bf16 v[48:51], v[184:187], v[224:227], v[48:51]
	v_mfma_f32_16x16x32_bf16 v[16:19], v[192:195], v[224:227], v[16:19]
	s_barrier
	s_setprio 0
	s_add_i32 s8, s14, s60
	v_lshl_add_u64 v[162:163], s[54:55], 0, v[128:129]
	s_mov_b32 m0, s8
	ds_read_b128 v[196:199], v166 offset:16384
	ds_read_b128 v[200:203], v166 offset:17408
	ds_read_b128 v[204:207], v166 offset:18432
	ds_read_b128 v[208:211], v166 offset:19456
	ds_read_b128 v[212:215], v166 offset:20480
	ds_read_b128 v[216:219], v166 offset:21504
	ds_read_b128 v[220:223], v166 offset:22528
	ds_read_b128 v[224:227], v166 offset:23552
	global_load_lds_dwordx4 v[162:163], off
	s_add_i32 m0, s8, 0x2000
	s_add_u32 s8, s54, 0xb0000
	v_lshl_add_u64 v[228:229], s[54:55], 0, v[138:139]
	s_addc_u32 s9, s55, 0
	s_add_i32 s12, s12, s60
	global_load_lds_dwordx4 v[228:229], off
	v_lshl_add_u64 v[230:231], s[8:9], 0, v[128:129]
	s_mov_b32 m0, s12
	v_lshl_add_u64 v[232:233], s[56:57], 0, v[138:139]
	global_load_lds_dwordx4 v[230:231], off
	v_lshl_add_u64 v[230:231], s[8:9], 0, v[138:139]
	s_add_i32 m0, s12, 0x2000
	s_nop 0
	global_load_lds_dwordx4 v[230:231], off
	v_lshl_add_u64 v[230:231], s[56:57], 0, v[128:129]
	s_mov_b32 m0, s61
	s_nop 0
	global_load_lds_dwordx4 v[230:231], off
	s_mov_b32 m0, s63
	s_nop 0
	global_load_lds_dwordx4 v[232:233], off
	s_waitcnt vmcnt(8)
	s_waitcnt lgkmcnt(0)
	s_setprio 1
	s_barrier
; #define PG8_STAGE(bufoff, gbase, voff) do { _Pragma("unroll") for (int _i = 0; _i < 2; ++_i) \
;         __builtin_amdgcn_global_load_lds((const unsigned*)((const char*)(gbase) + (voff)[_i]), (LAS unsigned*)(lds + (bufoff) + ldsw + _i * 8192), 16, 0, 0); } while (0)
; #define PG8_LDA(dst, b, h) do { _Pragma("unroll") for (int m = 0; m < 4; ++m) _Pragma("unroll") for (int k = 0; k < 2; ++k) dst[m][k] = *(const LAS bf16x8*)(lds + PG8_SA(b, h) + aoff + m * 2048 + k * 1024); } while (0)
; #define PG8_LDB(dst, b, h) do { _Pragma("unroll") for (int n = 0; n < 2; ++n) _Pragma("unroll") for (int k = 0; k < 2; ++k) dst[n][k] = *(const LAS bf16x8*)(lds + PG8_SB(b, h) + boff + n * 2048 + k * 1024); } while (0)
; #define PG8_MMA(ai, bj, At, Bt) do { __builtin_amdgcn_s_setprio(1); _Pragma("unroll") for (int m = 0; m < 4; ++m) _Pragma("unroll") for (int n = 0; n < 2; ++n) _Pragma("unroll") for (int k = 0; k < 2; ++k) \
;         acc[ai][bj][m][n] = __builtin_amdgcn_mfma_f32_16x16x32_bf16(Bt[n][k], At[m][k], acc[ai][bj][m][n], 0, 0, 0); __builtin_amdgcn_s_setprio(0); } while (0)
; #define PG8_WAIT_V(n) asm volatile("s_waitcnt vmcnt(" #n ")" ::: "memory")
; #define PG8_WAIT_L(n) asm volatile("s_waitcnt lgkmcnt(" #n ")" ::: "memory")
; #define PG8_BAR __builtin_amdgcn_s_barrier()
; #define PG8_SCHED __builtin_amdgcn_sched_barrier(0)
; template <class Epi, class Sched>
; __device__ __forceinline__ void gemm_phase(LAS unsigned char* lds, const int K, const Sched& S, const Epi& E) {
;     ...
;             PG8_WAIT_V(8); PG8_WAIT_L(0); PG8_BAR; PG8_MMA(1, 0, At, B0); PG8_MMA(1, 1, At, B1); PG8_BAR; PG8_SCHED;
;             PG8_LDB(B0, 1, 0); PG8_LDB(B1, 1, 1); PG8_SCHED; PG8_LDA(At, 1, 0); PG8_STAGE(PG8_SA(0, 1), a2 + hstep, voffA);
;             PG8_WAIT_V(8); PG8_WAIT_L(0); PG8_BAR; PG8_MMA(0, 0, At, B0); PG8_MMA(0, 1, At, B1); PG8_BAR; PG8_SCHED;
	v_mfma_f32_16x16x32_bf16 v[108:111], v[146:149], v[196:199], v[108:111]
	v_mfma_f32_16x16x32_bf16 v[76:79], v[154:157], v[196:199], v[76:79]
	v_mfma_f32_16x16x32_bf16 v[104:107], v[146:149], v[204:207], v[104:107]
	v_mfma_f32_16x16x32_bf16 v[72:75], v[154:157], v[204:207], v[72:75]
	v_mfma_f32_16x16x32_bf16 v[100:103], v[146:149], v[212:215], v[100:103]
	v_mfma_f32_16x16x32_bf16 v[68:71], v[154:157], v[212:215], v[68:71]
	v_mfma_f32_16x16x32_bf16 v[96:99], v[146:149], v[220:223], v[96:99]
	v_mfma_f32_16x16x32_bf16 v[64:67], v[154:157], v[220:223], v[64:67]
	v_mfma_f32_16x16x32_bf16 v[108:111], v[150:153], v[200:203], v[108:111]
	v_mfma_f32_16x16x32_bf16 v[76:79], v[158:161], v[200:203], v[76:79]
	v_mfma_f32_16x16x32_bf16 v[104:107], v[150:153], v[208:211], v[104:107]
	v_mfma_f32_16x16x32_bf16 v[72:75], v[158:161], v[208:211], v[72:75]
	v_mfma_f32_16x16x32_bf16 v[100:103], v[150:153], v[216:219], v[100:103]
	v_mfma_f32_16x16x32_bf16 v[68:71], v[158:161], v[216:219], v[68:71]
	v_mfma_f32_16x16x32_bf16 v[96:99], v[150:153], v[224:227], v[96:99]
	v_mfma_f32_16x16x32_bf16 v[64:67], v[158:161], v[224:227], v[64:67]
	s_setprio 0
	s_setprio 1
	v_mfma_f32_16x16x32_bf16 v[44:47], v[180:183], v[196:199], v[44:47]
	v_mfma_f32_16x16x32_bf16 v[12:15], v[188:191], v[196:199], v[12:15]
	v_mfma_f32_16x16x32_bf16 v[40:43], v[180:183], v[204:207], v[40:43]
	v_mfma_f32_16x16x32_bf16 v[8:11], v[188:191], v[204:207], v[8:11]
	v_mfma_f32_16x16x32_bf16 v[36:39], v[180:183], v[212:215], v[36:39]
	v_mfma_f32_16x16x32_bf16 v[4:7], v[188:191], v[212:215], v[4:7]
	v_mfma_f32_16x16x32_bf16 v[32:35], v[180:183], v[220:223], v[32:35]
	v_mfma_f32_16x16x32_bf16 v[0:3], v[188:191], v[220:223], v[0:3]
	v_mfma_f32_16x16x32_bf16 v[44:47], v[184:187], v[200:203], v[44:47]
	v_mfma_f32_16x16x32_bf16 v[12:15], v[192:195], v[200:203], v[12:15]
	v_mfma_f32_16x16x32_bf16 v[40:43], v[184:187], v[208:211], v[40:43]
	v_mfma_f32_16x16x32_bf16 v[8:11], v[192:195], v[208:211], v[8:11]
	v_mfma_f32_16x16x32_bf16 v[36:39], v[184:187], v[216:219], v[36:39]
	v_mfma_f32_16x16x32_bf16 v[4:7], v[192:195], v[216:219], v[4:7]
	v_mfma_f32_16x16x32_bf16 v[32:35], v[184:187], v[224:227], v[32:35]
	v_mfma_f32_16x16x32_bf16 v[0:3], v[192:195], v[224:227], v[0:3]
	s_barrier
	s_setprio 0
	s_add_i32 s12, 0, 0x18000
	s_add_i32 s14, 0, 0x1c000
	v_add_u32_e32 v158, s12, v164
	v_add_u32_e32 v167, s14, v164
	ds_read_b128 v[146:149], v158
	ds_read_b128 v[150:153], v158 offset:1024
	ds_read_b128 v[154:157], v158 offset:2048
	ds_read_b128 v[158:161], v158 offset:3072
	ds_read_b128 v[180:183], v167
	ds_read_b128 v[184:187], v167 offset:1024
	ds_read_b128 v[188:191], v167 offset:2048
	ds_read_b128 v[192:195], v167 offset:3072
	s_add_u32 s8, s56, 0xb0000
	s_addc_u32 s9, s57, 0
	s_mov_b32 m0, s64
	v_lshl_add_u64 v[234:235], s[8:9], 0, v[128:129]
	ds_read_b128 v[196:199], v166 offset:32768
	ds_read_b128 v[200:203], v166 offset:33792
	ds_read_b128 v[204:207], v166 offset:34816
	ds_read_b128 v[208:211], v166 offset:35840
	ds_read_b128 v[212:215], v166 offset:36864
	ds_read_b128 v[216:219], v166 offset:37888
	ds_read_b128 v[220:223], v166 offset:38912
	ds_read_b128 v[224:227], v166 offset:39936
	global_load_lds_dwordx4 v[234:235], off
	v_lshl_add_u64 v[234:235], s[8:9], 0, v[138:139]
	s_mov_b32 m0, s65
	s_nop 0
	global_load_lds_dwordx4 v[234:235], off
	s_waitcnt vmcnt(8)
	s_waitcnt lgkmcnt(0)
	s_setprio 1
	s_barrier
	v_mfma_f32_16x16x32_bf16 v[124:127], v[146:149], v[196:199], v[124:127]
	v_mfma_f32_16x16x32_bf16 v[92:95], v[154:157], v[196:199], v[92:95]
	v_mfma_f32_16x16x32_bf16 v[120:123], v[146:149], v[204:207], v[120:123]
	v_mfma_f32_16x16x32_bf16 v[88:91], v[154:157], v[204:207], v[88:91]
	v_mfma_f32_16x16x32_bf16 v[116:119], v[146:149], v[212:215], v[116:119]
	v_mfma_f32_16x16x32_bf16 v[84:87], v[154:157], v[212:215], v[84:87]
	v_mfma_f32_16x16x32_bf16 v[112:115], v[146:149], v[220:223], v[112:115]
	v_mfma_f32_16x16x32_bf16 v[80:83], v[154:157], v[220:223], v[80:83]
	v_mfma_f32_16x16x32_bf16 v[124:127], v[150:153], v[200:203], v[124:127]
	v_mfma_f32_16x16x32_bf16 v[92:95], v[158:161], v[200:203], v[92:95]
	v_mfma_f32_16x16x32_bf16 v[120:123], v[150:153], v[208:211], v[120:123]
	v_mfma_f32_16x16x32_bf16 v[88:91], v[158:161], v[208:211], v[88:91]
	v_mfma_f32_16x16x32_bf16 v[116:119], v[150:153], v[216:219], v[116:119]
	v_mfma_f32_16x16x32_bf16 v[84:87], v[158:161], v[216:219], v[84:87]
	v_mfma_f32_16x16x32_bf16 v[112:115], v[150:153], v[224:227], v[112:115]
	v_mfma_f32_16x16x32_bf16 v[80:83], v[158:161], v[224:227], v[80:83]
	s_setprio 0
	s_setprio 1
	v_mfma_f32_16x16x32_bf16 v[60:63], v[180:183], v[196:199], v[60:63]
	v_mfma_f32_16x16x32_bf16 v[28:31], v[188:191], v[196:199], v[28:31]
	v_mfma_f32_16x16x32_bf16 v[56:59], v[180:183], v[204:207], v[56:59]
	v_mfma_f32_16x16x32_bf16 v[24:27], v[188:191], v[204:207], v[24:27]
	v_mfma_f32_16x16x32_bf16 v[52:55], v[180:183], v[212:215], v[52:55]
	v_mfma_f32_16x16x32_bf16 v[20:23], v[188:191], v[212:215], v[20:23]
	v_mfma_f32_16x16x32_bf16 v[48:51], v[180:183], v[220:223], v[48:51]
	v_mfma_f32_16x16x32_bf16 v[16:19], v[188:191], v[220:223], v[16:19]
	v_mfma_f32_16x16x32_bf16 v[60:63], v[184:187], v[200:203], v[60:63]
	v_mfma_f32_16x16x32_bf16 v[28:31], v[192:195], v[200:203], v[28:31]
	v_mfma_f32_16x16x32_bf16 v[56:59], v[184:187], v[208:211], v[56:59]
	v_mfma_f32_16x16x32_bf16 v[24:27], v[192:195], v[208:211], v[24:27]
	v_mfma_f32_16x16x32_bf16 v[52:55], v[184:187], v[216:219], v[52:55]
	v_mfma_f32_16x16x32_bf16 v[20:23], v[192:195], v[216:219], v[20:23]
	v_mfma_f32_16x16x32_bf16 v[48:51], v[184:187], v[224:227], v[48:51]
	v_mfma_f32_16x16x32_bf16 v[16:19], v[192:195], v[224:227], v[16:19]
	s_barrier
; #define PG8_STAGE(bufoff, gbase, voff) do { _Pragma("unroll") for (int _i = 0; _i < 2; ++_i) \
;         __builtin_amdgcn_global_load_lds((const unsigned*)((const char*)(gbase) + (voff)[_i]), (LAS unsigned*)(lds + (bufoff) + ldsw + _i * 8192), 16, 0, 0); } while (0)
; #define PG8_LDA(dst, b, h) do { _Pragma("unroll") for (int m = 0; m < 4; ++m) _Pragma("unroll") for (int k = 0; k < 2; ++k) dst[m][k] = *(const LAS bf16x8*)(lds + PG8_SA(b, h) + aoff + m * 2048 + k * 1024); } while (0)
; #define PG8_MMA(ai, bj, At, Bt) do { __builtin_amdgcn_s_setprio(1); _Pragma("unroll") for (int m = 0; m < 4; ++m) _Pragma("unroll") for (int n = 0; n < 2; ++n) _Pragma("unroll") for (int k = 0; k < 2; ++k) \
;         acc[ai][bj][m][n] = __builtin_amdgcn_mfma_f32_16x16x32_bf16(Bt[n][k], At[m][k], acc[ai][bj][m][n], 0, 0, 0); __builtin_amdgcn_s_setprio(0); } while (0)
; #define PG8_WAIT_V(n) asm volatile("s_waitcnt vmcnt(" #n ")" ::: "memory")
; #define PG8_WAIT_L(n) asm volatile("s_waitcnt lgkmcnt(" #n ")" ::: "memory")
; #define PG8_BAR __builtin_amdgcn_s_barrier()
; #define PG8_SCHED __builtin_amdgcn_sched_barrier(0)
; template <class Epi, class Sched>
; __device__ __forceinline__ void gemm_phase(LAS unsigned char* lds, const int K, const Sched& S, const Epi& E) {
;     ...
;             PG8_LDA(At, 1, 1); PG8_STAGE(PG8_SB(1, 0), b3, voffB); PG8_STAGE(PG8_SB(1, 1), b3 + hstep, voffB); PG8_STAGE(PG8_SA(1, 0), a3, voffA);
;             PG8_WAIT_V(8); PG8_WAIT_L(0); PG8_BAR; PG8_MMA(1, 0, At, B0); PG8_MMA(1, 1, At, B1); PG8_BAR; PG8_SCHED;
;         }
;         if (wr == 0) PG8_BAR;
	s_setprio 0
	s_add_i32 s8, s12, s60
	v_lshl_add_u64 v[162:163], v[162:163], 0, s[36:37]
	s_mov_b32 m0, s8
	ds_read_b128 v[196:199], v166 offset:49152
	ds_read_b128 v[200:203], v166 offset:50176
	ds_read_b128 v[204:207], v166 offset:51200
	ds_read_b128 v[208:211], v166 offset:52224
	ds_read_b128 v[212:215], v166 offset:53248
	ds_read_b128 v[216:219], v166 offset:54272
	ds_read_b128 v[220:223], v166 offset:55296
	ds_read_b128 v[224:227], v166 offset:56320
	global_load_lds_dwordx4 v[162:163], off
	s_add_i32 m0, s8, 0x2000
	s_add_u32 s8, s54, 0xb0080
	v_lshl_add_u64 v[162:163], v[228:229], 0, s[36:37]
	s_addc_u32 s9, s55, 0
	s_add_i32 s12, s14, s60
	global_load_lds_dwordx4 v[162:163], off
	v_lshl_add_u64 v[162:163], s[8:9], 0, v[128:129]
	s_mov_b32 m0, s12
	s_nop 0
	global_load_lds_dwordx4 v[162:163], off
	v_lshl_add_u64 v[162:163], s[8:9], 0, v[138:139]
	s_add_i32 m0, s12, 0x2000
	s_nop 0
	global_load_lds_dwordx4 v[162:163], off
	v_lshl_add_u64 v[162:163], v[230:231], 0, s[36:37]
	s_mov_b32 m0, s68
	s_nop 0
	global_load_lds_dwordx4 v[162:163], off
	v_lshl_add_u64 v[162:163], v[232:233], 0, s[36:37]
	s_mov_b32 m0, s69
	s_nop 0
	global_load_lds_dwordx4 v[162:163], off
	s_waitcnt vmcnt(8)
	s_waitcnt lgkmcnt(0)
	s_setprio 1
	s_barrier
	v_mfma_f32_16x16x32_bf16 v[108:111], v[146:149], v[196:199], v[108:111]
	v_mfma_f32_16x16x32_bf16 v[76:79], v[154:157], v[196:199], v[76:79]
	v_mfma_f32_16x16x32_bf16 v[104:107], v[146:149], v[204:207], v[104:107]
	v_mfma_f32_16x16x32_bf16 v[72:75], v[154:157], v[204:207], v[72:75]
	v_mfma_f32_16x16x32_bf16 v[100:103], v[146:149], v[212:215], v[100:103]
	v_mfma_f32_16x16x32_bf16 v[68:71], v[154:157], v[212:215], v[68:71]
	v_mfma_f32_16x16x32_bf16 v[96:99], v[146:149], v[220:223], v[96:99]
	v_mfma_f32_16x16x32_bf16 v[64:67], v[154:157], v[220:223], v[64:67]
	v_mfma_f32_16x16x32_bf16 v[108:111], v[150:153], v[200:203], v[108:111]
	v_mfma_f32_16x16x32_bf16 v[76:79], v[158:161], v[200:203], v[76:79]
	v_mfma_f32_16x16x32_bf16 v[104:107], v[150:153], v[208:211], v[104:107]
	v_mfma_f32_16x16x32_bf16 v[72:75], v[158:161], v[208:211], v[72:75]
	v_mfma_f32_16x16x32_bf16 v[100:103], v[150:153], v[216:219], v[100:103]
	v_mfma_f32_16x16x32_bf16 v[68:71], v[158:161], v[216:219], v[68:71]
	v_mfma_f32_16x16x32_bf16 v[96:99], v[150:153], v[224:227], v[96:99]
	v_mfma_f32_16x16x32_bf16 v[64:67], v[158:161], v[224:227], v[64:67]
	s_setprio 0
	s_setprio 1
	v_mfma_f32_16x16x32_bf16 v[44:47], v[180:183], v[196:199], v[44:47]
	v_mfma_f32_16x16x32_bf16 v[12:15], v[188:191], v[196:199], v[12:15]
	v_mfma_f32_16x16x32_bf16 v[40:43], v[180:183], v[204:207], v[40:43]
	v_mfma_f32_16x16x32_bf16 v[8:11], v[188:191], v[204:207], v[8:11]
	v_mfma_f32_16x16x32_bf16 v[36:39], v[180:183], v[212:215], v[36:39]
	v_mfma_f32_16x16x32_bf16 v[4:7], v[188:191], v[212:215], v[4:7]
	v_mfma_f32_16x16x32_bf16 v[32:35], v[180:183], v[220:223], v[32:35]
	v_mfma_f32_16x16x32_bf16 v[0:3], v[188:191], v[220:223], v[0:3]
	v_mfma_f32_16x16x32_bf16 v[44:47], v[184:187], v[200:203], v[44:47]
	v_mfma_f32_16x16x32_bf16 v[12:15], v[192:195], v[200:203], v[12:15]
	v_mfma_f32_16x16x32_bf16 v[40:43], v[184:187], v[208:211], v[40:43]
	v_mfma_f32_16x16x32_bf16 v[8:11], v[192:195], v[208:211], v[8:11]
	v_mfma_f32_16x16x32_bf16 v[36:39], v[184:187], v[216:219], v[36:39]
	v_mfma_f32_16x16x32_bf16 v[4:7], v[192:195], v[216:219], v[4:7]
	v_mfma_f32_16x16x32_bf16 v[32:35], v[184:187], v[224:227], v[32:35]
	v_mfma_f32_16x16x32_bf16 v[0:3], v[192:195], v[224:227], v[0:3]
	s_barrier
	s_setprio 0
	s_add_u32 s10, s10, 0x100
	s_addc_u32 s11, s11, 0
	s_cmp_ge_i32 s13, s51
	s_mov_b64 s[8:9], s[52:53]
	s_mov_b32 s12, s13
	s_cbranch_scc0 .LBB0_1073
	s_and_b64 vcc, exec, s[40:41]
	s_cbranch_vccz .LBB0_1076
